# attention context-chunk row max as four v_max3_f32 chains (34 instead of 73 instructions per unit), on top of the previous best
# baseline (speedup 1.0000x reference)
; #define LAS __attribute__((address_space(3)))
; #define MFMA16(a, b, c) __builtin_amdgcn_mfma_f32_16x16x32_bf16((a), (b), (c), 0, 0, 0)
; #define ATTN_SB() __builtin_amdgcn_sched_barrier(0)
; __device__ __forceinline__ void attn_unit(int u, const bf16_t* KB, const bf16_t* VT, const bf16_t* QU, bf16_t* OB, const LAS float* rpb_l, LAS unsigned char* ot, const LAS unsigned char* ckl, const LAS unsigned char* cvl, int lane_) {
;     ...
;         {
;             const int sw = (fr >> 2) * 2 + ((fr >> 1) & 1);
;             const LAS unsigned char* k0 = ckl + kk0 * 128 + ((fq ^ sw) << 4); const LAS unsigned char* k1 = ckl + kk0 * 128 + (((fq + 4) ^ sw) << 4);
; #pragma unroll
;             for (int j = 0; j < 8; ++j)
; #pragma unroll
;                 for (int t = 0; t < 2; ++t) { fb[j * 4 + t * 2] = *(const LAS bf16x8*)(k0 + j * 4096 + t * 512); fb[j * 4 + t * 2 + 1] = *(const LAS bf16x8*)(k1 + j * 4096 + t * 512); }
;         }
;         ATTN_SB();
; #pragma unroll
;         for (int j = 0; j < 8; ++j)
; #pragma unroll
;             for (int t = 0; t < 2; ++t) { f32x4 s = MFMA16(fb[j * 4 + t * 2], bq0, z4); s = MFMA16(fb[j * 4 + t * 2 + 1], bq1, s); st[j][t] = s; }
;         ATTN_SB();
;         {
;             const LAS unsigned char* v0 = cvl + fr * 512;
; #pragma unroll
;             for (int j = 0; j < 8; ++j) { const int xo = ((4 * j + fq) ^ fr) << 4;
; #pragma unroll
;                 for (int dt = 0; dt < 4; ++dt) fb[j * 4 + dt] = *(const LAS bf16x8*)(v0 + dt * 8192 + xo); }
;         }
.LBB0_904:
	s_lshl_b32 s4, s6, 15
	s_add_i32 s4, s4, 0
	v_lshlrev_b32_e32 v8, 1, v218
	v_bfe_u32 v9, v215, 1, 1
	v_lshl_add_u32 v10, v219, 7, s4
	v_bitop3_b32 v11, v8, v217, v9 bitop3:0x36
	v_add_u32_e32 v218, 4, v217
	v_lshl_add_u32 v124, v11, 4, v10
	v_bitop3_b32 v8, v8, v218, v9 bitop3:0x36
	v_lshl_add_u32 v132, v8, 4, v10
	ds_read_b128 v[8:11], v124
	ds_read_b128 v[12:15], v124 offset:512
	ds_read_b128 v[16:19], v132
	ds_read_b128 v[20:23], v132 offset:512
	ds_read_b128 v[24:27], v124 offset:4096
	ds_read_b128 v[28:31], v124 offset:4608
	ds_read_b128 v[32:35], v132 offset:4096
	ds_read_b128 v[36:39], v132 offset:4608
	ds_read_b128 v[40:43], v124 offset:8192
	ds_read_b128 v[44:47], v124 offset:8704
	ds_read_b128 v[48:51], v132 offset:8192
	ds_read_b128 v[52:55], v132 offset:8704
	ds_read_b128 v[56:59], v124 offset:12288
	ds_read_b128 v[60:63], v124 offset:12800
	ds_read_b128 v[64:67], v132 offset:12288
	ds_read_b128 v[68:71], v132 offset:12800
	ds_read_b128 v[72:75], v124 offset:16384
	ds_read_b128 v[76:79], v124 offset:16896
	ds_read_b128 v[80:83], v132 offset:16384
	ds_read_b128 v[84:87], v132 offset:16896
	ds_read_b128 v[88:91], v124 offset:20480
	ds_read_b128 v[92:95], v124 offset:20992
	ds_read_b128 v[96:99], v132 offset:20480
	ds_read_b128 v[100:103], v132 offset:20992
	ds_read_b128 v[104:107], v124 offset:24576
	ds_read_b128 v[108:111], v124 offset:25088
	ds_read_b128 v[112:115], v132 offset:24576
	ds_read_b128 v[116:119], v132 offset:25088
	ds_read_b128 v[120:123], v124 offset:28672
	ds_read_b128 v[124:127], v124 offset:29184
	ds_read_b128 v[128:131], v132 offset:28672
	ds_read_b128 v[224:227], v132 offset:29184
	s_add_i32 s4, s4, 0x10000
	s_waitcnt vmcnt(1) lgkmcnt(14)
	v_mfma_f32_16x16x32_bf16 v[8:11], v[8:11], v[0:3], 0
	s_waitcnt vmcnt(0)
	v_mfma_f32_16x16x32_bf16 v[228:231], v[16:19], v[4:7], v[8:11]
	v_mfma_f32_16x16x32_bf16 v[8:11], v[12:15], v[0:3], 0
	v_mfma_f32_16x16x32_bf16 v[232:235], v[20:23], v[4:7], v[8:11]
	v_mfma_f32_16x16x32_bf16 v[8:11], v[24:27], v[0:3], 0
	v_mfma_f32_16x16x32_bf16 v[196:199], v[32:35], v[4:7], v[8:11]
	v_mfma_f32_16x16x32_bf16 v[8:11], v[28:31], v[0:3], 0
	v_mfma_f32_16x16x32_bf16 v[192:195], v[36:39], v[4:7], v[8:11]
	v_mfma_f32_16x16x32_bf16 v[8:11], v[40:43], v[0:3], 0
	v_mfma_f32_16x16x32_bf16 v[188:191], v[48:51], v[4:7], v[8:11]
	v_mfma_f32_16x16x32_bf16 v[8:11], v[44:47], v[0:3], 0
	v_mfma_f32_16x16x32_bf16 v[184:187], v[52:55], v[4:7], v[8:11]
	v_mfma_f32_16x16x32_bf16 v[8:11], v[56:59], v[0:3], 0
	v_mfma_f32_16x16x32_bf16 v[180:183], v[64:67], v[4:7], v[8:11]
	v_mfma_f32_16x16x32_bf16 v[8:11], v[60:63], v[0:3], 0
	v_mfma_f32_16x16x32_bf16 v[172:175], v[68:71], v[4:7], v[8:11]
	v_mfma_f32_16x16x32_bf16 v[8:11], v[72:75], v[0:3], 0
	s_waitcnt lgkmcnt(13)
	v_mfma_f32_16x16x32_bf16 v[164:167], v[80:83], v[4:7], v[8:11]
	v_mfma_f32_16x16x32_bf16 v[8:11], v[76:79], v[0:3], 0
	s_waitcnt lgkmcnt(12)
	v_mfma_f32_16x16x32_bf16 v[160:163], v[84:87], v[4:7], v[8:11]
	s_waitcnt lgkmcnt(11)
	v_mfma_f32_16x16x32_bf16 v[8:11], v[88:91], v[0:3], 0
	s_waitcnt lgkmcnt(9)
	v_mfma_f32_16x16x32_bf16 v[148:151], v[96:99], v[4:7], v[8:11]
	v_mfma_f32_16x16x32_bf16 v[8:11], v[92:95], v[0:3], 0
	s_waitcnt lgkmcnt(8)
	v_mfma_f32_16x16x32_bf16 v[144:147], v[100:103], v[4:7], v[8:11]
	s_waitcnt lgkmcnt(7)
	v_mfma_f32_16x16x32_bf16 v[8:11], v[104:107], v[0:3], 0
	s_waitcnt lgkmcnt(5)
	v_mfma_f32_16x16x32_bf16 v[140:143], v[112:115], v[4:7], v[8:11]
	v_mfma_f32_16x16x32_bf16 v[8:11], v[108:111], v[0:3], 0
	s_waitcnt lgkmcnt(4)
	v_mfma_f32_16x16x32_bf16 v[136:139], v[116:119], v[4:7], v[8:11]
	s_waitcnt lgkmcnt(3)
	v_mfma_f32_16x16x32_bf16 v[8:11], v[120:123], v[0:3], 0
	s_waitcnt lgkmcnt(2)
	v_mfma_f32_16x16x32_bf16 v[0:3], v[124:127], v[0:3], 0
	s_waitcnt lgkmcnt(1)
	v_mfma_f32_16x16x32_bf16 v[132:135], v[128:131], v[4:7], v[8:11]
	s_waitcnt lgkmcnt(0)
	v_mfma_f32_16x16x32_bf16 v[128:131], v[224:227], v[4:7], v[0:3]
	s_nop 3
	v_lshl_add_u32 v0, v216, 9, s4
	v_xor_b32_e32 v1, v217, v216
	v_lshl_add_u32 v1, v1, 4, v0
	ds_read_b128 v[112:115], v1
	ds_read_b128 v[116:119], v1 offset:8192
	ds_read_b128 v[120:123], v1 offset:16384
	ds_read_b128 v[124:127], v1 offset:24576
	v_xor_b32_e32 v1, v218, v216
	v_lshl_add_u32 v1, v1, 4, v0
	ds_read_b128 v[96:99], v1
	ds_read_b128 v[100:103], v1 offset:8192
	ds_read_b128 v[104:107], v1 offset:16384
	ds_read_b128 v[108:111], v1 offset:24576
	v_add_u32_e32 v1, 8, v217
	v_xor_b32_e32 v1, v1, v216
	v_lshl_add_u32 v1, v1, 4, v0
	ds_read_b128 v[80:83], v1
	ds_read_b128 v[84:87], v1 offset:8192
	ds_read_b128 v[88:91], v1 offset:16384
	ds_read_b128 v[92:95], v1 offset:24576
	v_add_u32_e32 v1, 12, v217
	v_xor_b32_e32 v1, v1, v216
	v_lshl_add_u32 v1, v1, 4, v0
	ds_read_b128 v[64:67], v1
	ds_read_b128 v[68:71], v1 offset:8192
	ds_read_b128 v[72:75], v1 offset:16384
	ds_read_b128 v[76:79], v1 offset:24576
	v_add_u32_e32 v1, 16, v217
	v_xor_b32_e32 v1, v1, v216
	v_lshl_add_u32 v1, v1, 4, v0
	ds_read_b128 v[48:51], v1
	ds_read_b128 v[52:55], v1 offset:8192
	ds_read_b128 v[56:59], v1 offset:16384
	ds_read_b128 v[60:63], v1 offset:24576
	v_add_u32_e32 v1, 20, v217
	v_xor_b32_e32 v1, v1, v216
	v_lshl_add_u32 v1, v1, 4, v0
	ds_read_b128 v[32:35], v1
	ds_read_b128 v[36:39], v1 offset:8192
	ds_read_b128 v[40:43], v1 offset:16384
	ds_read_b128 v[44:47], v1 offset:24576
	v_add_u32_e32 v1, 24, v217
	v_xor_b32_e32 v1, v1, v216
	v_lshl_add_u32 v1, v1, 4, v0
	ds_read_b128 v[16:19], v1
	ds_read_b128 v[20:23], v1 offset:8192
	ds_read_b128 v[24:27], v1 offset:16384
	ds_read_b128 v[28:31], v1 offset:24576
	v_add_u32_e32 v1, 28, v217
	v_xor_b32_e32 v1, v1, v216
	v_lshl_add_u32 v0, v1, 4, v0
; __device__ __forceinline__ void attn_unit(int u, const bf16_t* KB, const bf16_t* VT, const bf16_t* QU, bf16_t* OB, const LAS float* rpb_l, LAS unsigned char* ot, const LAS unsigned char* ckl, const LAS unsigned char* cvl, int lane_) {
;     ...
;         float m2 = NEG;
; #pragma unroll
;         for (int g = 0; g < 8; ++g)
; #pragma unroll
;             for (int t = 0; t < 2; ++t) m2 = fmaxf(m2, fmaxf(fmaxf(st[g][t][0], st[g][t][1]), fmaxf(st[g][t][2], st[g][t][3])));
;         m2 = fmaxf(m2, __shfl_xor(m2, 16)); m2 = fmaxf(m2, __shfl_xor(m2, 32));
;         const float mn = fmaxf(m, m2);
;         const float alpha = __builtin_amdgcn_exp2f(m - mn);
;         l *= alpha;
; #pragma unroll
;         for (int e = 0; e < 4; ++e) { const float aq = __shfl(alpha, 4 * fq + e);
; #pragma unroll
;             for (int dt = 0; dt < 4; ++dt) o[dt][e] *= aq; }
; #pragma unroll
;         for (int g = 0; g < 8; ++g)
; #pragma unroll
;             for (int t = 0; t < 2; ++t)
; #pragma unroll
;                 for (int e = 0; e < 4; ++e) { const float p = __builtin_amdgcn_exp2f(st[g][t][e] - mn); st[g][t][e] = p; l += p; }
	ds_read_b128 v[4:7], v0
	ds_read_b128 v[8:11], v0 offset:8192
	ds_read_b128 v[12:15], v0 offset:16384
	ds_read_b128 v[0:3], v0 offset:24576
	v_cmp_lt_i32_e32 vcc, v220, v202
	v_max3_f32 v218, v231, v228, v199
	v_max3_f32 v219, v230, v229, v198
	v_max3_f32 v223, v235, v232, v195
	v_max3_f32 v224, v234, v233, v194
	v_max3_f32 v218, v218, v196, v191
	v_max3_f32 v219, v219, v197, v190
	v_max3_f32 v223, v223, v192, v187
	v_max3_f32 v224, v224, v193, v186
	v_max3_f32 v218, v218, v188, v183
	v_max3_f32 v219, v219, v189, v182
	v_max3_f32 v223, v223, v184, v175
	v_max3_f32 v224, v224, v185, v174
	v_max3_f32 v218, v218, v180, v167
	v_max3_f32 v219, v219, v181, v166
	v_max3_f32 v223, v223, v172, v163
	v_max3_f32 v224, v224, v173, v162
	v_max3_f32 v218, v218, v164, v151
	v_max3_f32 v219, v219, v165, v150
	v_max3_f32 v223, v223, v160, v147
	v_max3_f32 v224, v224, v161, v146
	v_max3_f32 v218, v218, v148, v143
	v_max3_f32 v219, v219, v149, v142
	v_max3_f32 v223, v223, v144, v139
	v_max3_f32 v224, v224, v145, v138
	v_max3_f32 v218, v218, v140, v135
	v_max3_f32 v219, v219, v141, v134
	v_max3_f32 v223, v223, v136, v131
	v_max3_f32 v224, v224, v137, v130
	v_max_f32_e32 v218, v218, v132
	v_max_f32_e32 v219, v219, v133
	v_max_f32_e32 v223, v223, v128
	v_max_f32_e32 v224, v224, v129
	v_max3_f32 v219, v219, v223, v224
	v_max3_f32 v218, v218, s64, v219
	v_lshlrev_b32_e32 v224, 2, v217
	v_cndmask_b32_e32 v219, v204, v220, vcc
	v_lshlrev_b32_e32 v220, 2, v219
	ds_bpermute_b32 v219, v220, v218
	v_cmp_lt_i32_e32 vcc, v221, v202
	v_and_b32_e32 v225, 0x3fffffc0, v204
	s_waitcnt lgkmcnt(0)
	v_max_f32_e32 v219, v219, v219
	v_cndmask_b32_e32 v202, v204, v221, vcc
	v_max_f32_e32 v218, v218, v219
	v_lshlrev_b32_e32 v202, 2, v202
	ds_bpermute_b32 v219, v202, v218
	v_and_or_b32 v204, v224, 60, v225
	v_lshlrev_b32_e32 v226, 2, v204
	s_waitcnt lgkmcnt(0)
	v_max3_f32 v221, v205, v218, v219
	v_sub_f32_e32 v205, v205, v221
	v_exp_f32_e32 v223, v205
	v_sub_f32_e32 v227, v228, v221
	v_exp_f32_e32 v227, v227
	v_sub_f32_e32 v228, v234, v221
	ds_bpermute_b32 v204, v226, v223
	ds_bpermute_b32 v205, v226, v223 offset:4
	ds_bpermute_b32 v218, v226, v223 offset:8
	ds_bpermute_b32 v219, v226, v223 offset:12
	v_exp_f32_e32 v228, v228
	v_sub_f32_e32 v196, v196, v221
	s_waitcnt lgkmcnt(2)
	v_pk_mul_f32 v[176:177], v[176:177], v[204:205]
	v_pk_mul_f32 v[168:169], v[168:169], v[204:205]
	v_pk_mul_f32 v[152:153], v[152:153], v[204:205]
	v_pk_mul_f32 v[156:157], v[156:157], v[204:205]
	v_sub_f32_e32 v205, v229, v221
	s_waitcnt lgkmcnt(0)
	v_pk_mul_f32 v[178:179], v[178:179], v[218:219]
	v_pk_mul_f32 v[170:171], v[170:171], v[218:219]
	v_pk_mul_f32 v[154:155], v[154:155], v[218:219]
	v_pk_mul_f32 v[158:159], v[158:159], v[218:219]
	v_exp_f32_e32 v205, v205
	v_sub_f32_e32 v218, v230, v221
	v_exp_f32_e32 v218, v218
	v_sub_f32_e32 v219, v231, v221
	v_fma_f32 v204, v222, v223, v227
	v_exp_f32_e32 v219, v219
	v_sub_f32_e32 v222, v232, v221
	v_exp_f32_e32 v222, v222
	v_sub_f32_e32 v223, v233, v221
	v_add_f32_e32 v204, v205, v204
	v_exp_f32_e32 v223, v223
	v_add_f32_e32 v204, v218, v204
	v_sub_f32_e32 v229, v235, v221
	v_add_f32_e32 v204, v219, v204
	v_exp_f32_e32 v229, v229
	v_add_f32_e32 v204, v222, v204
	v_exp_f32_e32 v196, v196
	v_sub_f32_e32 v197, v197, v221
	v_add_f32_e32 v204, v223, v204
	v_exp_f32_e32 v197, v197
	v_sub_f32_e32 v198, v198, v221
	v_add_f32_e32 v204, v228, v204
	v_exp_f32_e32 v198, v198
	v_sub_f32_e32 v199, v199, v221
	v_add_f32_e32 v204, v229, v204
	v_exp_f32_e32 v199, v199
	v_sub_f32_e32 v192, v192, v221
	v_add_f32_e32 v204, v196, v204
	v_exp_f32_e32 v192, v192
	v_sub_f32_e32 v193, v193, v221
	v_add_f32_e32 v204, v197, v204
	v_exp_f32_e32 v193, v193
	v_sub_f32_e32 v194, v194, v221
	v_add_f32_e32 v204, v198, v204
	v_exp_f32_e32 v194, v194
	v_sub_f32_e32 v195, v195, v221
	v_add_f32_e32 v204, v199, v204
	v_exp_f32_e32 v195, v195
	v_sub_f32_e32 v188, v188, v221
	v_add_f32_e32 v204, v192, v204
	v_exp_f32_e32 v188, v188
	v_sub_f32_e32 v189, v189, v221
	v_add_f32_e32 v204, v193, v204
	v_exp_f32_e32 v189, v189
	v_sub_f32_e32 v190, v190, v221
	v_add_f32_e32 v204, v194, v204
	v_exp_f32_e32 v190, v190
	v_sub_f32_e32 v191, v191, v221
	v_add_f32_e32 v204, v195, v204
	v_exp_f32_e32 v191, v191
	v_sub_f32_e32 v184, v184, v221
	v_add_f32_e32 v204, v188, v204
	v_exp_f32_e32 v184, v184
	v_sub_f32_e32 v185, v185, v221
	v_add_f32_e32 v204, v189, v204
	v_exp_f32_e32 v185, v185
	v_sub_f32_e32 v186, v186, v221
	v_add_f32_e32 v204, v190, v204
	v_exp_f32_e32 v186, v186
	v_sub_f32_e32 v187, v187, v221
	v_add_f32_e32 v204, v191, v204
	v_exp_f32_e32 v187, v187
	v_sub_f32_e32 v180, v180, v221
	v_add_f32_e32 v204, v184, v204
	v_exp_f32_e32 v180, v180
	v_sub_f32_e32 v181, v181, v221
	v_add_f32_e32 v204, v185, v204
	v_exp_f32_e32 v181, v181
	v_sub_f32_e32 v182, v182, v221
	v_add_f32_e32 v204, v186, v204
	v_exp_f32_e32 v182, v182
	v_sub_f32_e32 v183, v183, v221
	v_add_f32_e32 v204, v187, v204
	v_exp_f32_e32 v183, v183
	v_sub_f32_e32 v172, v172, v221
	v_add_f32_e32 v204, v180, v204
	v_exp_f32_e32 v172, v172
	v_sub_f32_e32 v173, v173, v221
	v_add_f32_e32 v204, v181, v204
	v_exp_f32_e32 v173, v173
	v_sub_f32_e32 v174, v174, v221
	v_add_f32_e32 v204, v182, v204
	v_exp_f32_e32 v174, v174
	v_sub_f32_e32 v175, v175, v221
	v_add_f32_e32 v204, v183, v204
	v_exp_f32_e32 v175, v175
	v_sub_f32_e32 v164, v164, v221
	v_add_f32_e32 v204, v172, v204
	v_exp_f32_e32 v164, v164
	v_sub_f32_e32 v165, v165, v221
	v_add_f32_e32 v204, v173, v204
	v_exp_f32_e32 v165, v165
	v_sub_f32_e32 v166, v166, v221
	v_add_f32_e32 v204, v174, v204
	v_exp_f32_e32 v166, v166
	v_sub_f32_e32 v167, v167, v221
	v_add_f32_e32 v204, v175, v204
; __device__ __forceinline__ unsigned cvtpk_s(float lo, float hi) { f32x2_t v = {lo, hi}; bf16x2_t b = __builtin_convertvector(v, bf16x2_t); return __builtin_bit_cast(unsigned, b); }
; #define MFMA16(a, b, c) __builtin_amdgcn_mfma_f32_16x16x32_bf16((a), (b), (c), 0, 0, 0)
; #define ATTN_SB() __builtin_amdgcn_sched_barrier(0)
; __device__ __forceinline__ void attn_unit(int u, const bf16_t* KB, const bf16_t* VT, const bf16_t* QU, bf16_t* OB, const LAS float* rpb_l, LAS unsigned char* ot, const LAS unsigned char* ckl, const LAS unsigned char* cvl, int lane_) {
;     ...
;         for (int g = 0; g < 8; ++g)
; #pragma unroll
;             for (int t = 0; t < 2; ++t)
; #pragma unroll
;                 for (int e = 0; e < 4; ++e) { const float p = __builtin_amdgcn_exp2f(st[g][t][e] - mn); st[g][t][e] = p; l += p; }
;         ATTN_SB();
; #pragma unroll
;         for (int j = 0; j < 8; ++j) {
;             u32x4 pw; pw.x = cvtpk_s(st[j][0][0], st[j][0][1]); pw.y = cvtpk_s(st[j][0][2], st[j][0][3]); pw.z = cvtpk_s(st[j][1][0], st[j][1][1]); pw.w = cvtpk_s(st[j][1][2], st[j][1][3]);
;             const bf16x8 pa = __builtin_bit_cast(bf16x8, pw);
; #pragma unroll
;             for (int dt = 0; dt < 4; ++dt) o[dt] = MFMA16(pa, fb[j * 4 + dt], o[dt]);
;         }
;     }
;     __builtin_amdgcn_sched_barrier(0);
;     l += __shfl_xor(l, 16); l += __shfl_xor(l, 32);
	v_exp_f32_e32 v167, v167
	v_sub_f32_e32 v160, v160, v221
	v_add_f32_e32 v204, v164, v204
	v_exp_f32_e32 v160, v160
	v_sub_f32_e32 v161, v161, v221
	v_add_f32_e32 v204, v165, v204
	v_exp_f32_e32 v161, v161
	v_sub_f32_e32 v162, v162, v221
	v_add_f32_e32 v204, v166, v204
	v_exp_f32_e32 v162, v162
	v_sub_f32_e32 v163, v163, v221
	v_add_f32_e32 v204, v167, v204
	v_exp_f32_e32 v163, v163
	v_sub_f32_e32 v148, v148, v221
	v_add_f32_e32 v204, v160, v204
	v_exp_f32_e32 v148, v148
	v_sub_f32_e32 v149, v149, v221
	v_add_f32_e32 v204, v161, v204
	v_exp_f32_e32 v149, v149
	v_sub_f32_e32 v150, v150, v221
	v_add_f32_e32 v204, v162, v204
	v_exp_f32_e32 v150, v150
	v_sub_f32_e32 v151, v151, v221
	v_add_f32_e32 v204, v163, v204
	v_exp_f32_e32 v151, v151
	v_sub_f32_e32 v144, v144, v221
	v_add_f32_e32 v204, v148, v204
	v_exp_f32_e32 v144, v144
	v_sub_f32_e32 v145, v145, v221
	v_add_f32_e32 v204, v149, v204
	v_exp_f32_e32 v145, v145
	v_sub_f32_e32 v146, v146, v221
	v_add_f32_e32 v204, v150, v204
	v_exp_f32_e32 v146, v146
	v_sub_f32_e32 v147, v147, v221
	v_add_f32_e32 v204, v151, v204
	v_exp_f32_e32 v147, v147
	v_sub_f32_e32 v140, v140, v221
	v_add_f32_e32 v204, v144, v204
	v_exp_f32_e32 v140, v140
	v_sub_f32_e32 v141, v141, v221
	v_add_f32_e32 v204, v145, v204
	v_exp_f32_e32 v141, v141
	v_sub_f32_e32 v142, v142, v221
	v_add_f32_e32 v204, v146, v204
	v_exp_f32_e32 v142, v142
	v_sub_f32_e32 v143, v143, v221
	v_add_f32_e32 v204, v147, v204
	v_exp_f32_e32 v143, v143
	v_sub_f32_e32 v136, v136, v221
	v_add_f32_e32 v204, v140, v204
	v_exp_f32_e32 v136, v136
	v_sub_f32_e32 v137, v137, v221
	v_add_f32_e32 v204, v141, v204
	v_exp_f32_e32 v137, v137
	v_sub_f32_e32 v138, v138, v221
	v_add_f32_e32 v204, v142, v204
	v_exp_f32_e32 v138, v138
	v_sub_f32_e32 v139, v139, v221
	v_add_f32_e32 v204, v143, v204
	v_exp_f32_e32 v139, v139
	v_sub_f32_e32 v132, v132, v221
	v_add_f32_e32 v204, v136, v204
	v_exp_f32_e32 v132, v132
	v_sub_f32_e32 v133, v133, v221
	v_add_f32_e32 v204, v137, v204
	v_exp_f32_e32 v133, v133
	v_sub_f32_e32 v134, v134, v221
	v_sub_f32_e32 v128, v128, v221
	v_add_f32_e32 v204, v138, v204
	v_exp_f32_e32 v134, v134
	v_sub_f32_e32 v135, v135, v221
	v_exp_f32_e32 v230, v128
	v_sub_f32_e32 v128, v129, v221
	v_add_f32_e32 v204, v139, v204
	v_exp_f32_e32 v135, v135
	v_exp_f32_e32 v231, v128
	v_sub_f32_e32 v128, v130, v221
	v_add_f32_e32 v204, v132, v204
	v_exp_f32_e32 v232, v128
	v_sub_f32_e32 v128, v131, v221
	v_exp_f32_e32 v221, v128
	v_add_f32_e32 v128, v133, v204
	v_add_f32_e32 v128, v134, v128
	v_add_f32_e32 v204, v135, v128
	v_cvt_pk_bf16_f32 v128, v227, v205
	v_cvt_pk_bf16_f32 v129, v218, v219
	v_cvt_pk_bf16_f32 v130, v222, v223
	v_cvt_pk_bf16_f32 v131, v228, v229
	s_nop 1
	v_mfma_f32_16x16x32_bf16 v[112:115], v[128:131], v[112:115], v[176:179]
	v_mfma_f32_16x16x32_bf16 v[116:119], v[128:131], v[116:119], v[168:171]
	v_mfma_f32_16x16x32_bf16 v[120:123], v[128:131], v[120:123], v[152:155]
	v_mfma_f32_16x16x32_bf16 v[124:127], v[128:131], v[124:127], v[156:159]
	v_cvt_pk_bf16_f32 v128, v196, v197
	v_cvt_pk_bf16_f32 v129, v198, v199
	v_cvt_pk_bf16_f32 v130, v192, v193
	v_cvt_pk_bf16_f32 v131, v194, v195
	s_nop 1
	v_mfma_f32_16x16x32_bf16 v[96:99], v[128:131], v[96:99], v[112:115]
	s_nop 2
	v_cvt_pk_bf16_f32 v112, v188, v189
	v_cvt_pk_bf16_f32 v113, v190, v191
	v_cvt_pk_bf16_f32 v114, v184, v185
	v_cvt_pk_bf16_f32 v115, v186, v187
	v_mfma_f32_16x16x32_bf16 v[100:103], v[128:131], v[100:103], v[116:119]
	s_nop 0
	v_mfma_f32_16x16x32_bf16 v[80:83], v[112:115], v[80:83], v[96:99]
	s_nop 2
	v_cvt_pk_bf16_f32 v96, v180, v181
	v_cvt_pk_bf16_f32 v97, v182, v183
	v_cvt_pk_bf16_f32 v98, v172, v173
	v_cvt_pk_bf16_f32 v99, v174, v175
	v_mfma_f32_16x16x32_bf16 v[104:107], v[128:131], v[104:107], v[120:123]
	v_mfma_f32_16x16x32_bf16 v[108:111], v[128:131], v[108:111], v[124:127]
	v_mfma_f32_16x16x32_bf16 v[64:67], v[96:99], v[64:67], v[80:83]
	s_nop 2
	v_cvt_pk_bf16_f32 v80, v164, v165
	v_cvt_pk_bf16_f32 v81, v166, v167
	v_cvt_pk_bf16_f32 v82, v160, v161
	v_cvt_pk_bf16_f32 v83, v162, v163
	v_mfma_f32_16x16x32_bf16 v[84:87], v[112:115], v[84:87], v[100:103]
	v_mfma_f32_16x16x32_bf16 v[88:91], v[112:115], v[88:91], v[104:107]
	v_mfma_f32_16x16x32_bf16 v[92:95], v[112:115], v[92:95], v[108:111]
	v_mfma_f32_16x16x32_bf16 v[48:51], v[80:83], v[48:51], v[64:67]
	s_nop 2
	v_cvt_pk_bf16_f32 v64, v148, v149
	v_cvt_pk_bf16_f32 v65, v150, v151
	v_cvt_pk_bf16_f32 v66, v144, v145
	v_cvt_pk_bf16_f32 v67, v146, v147
	v_mfma_f32_16x16x32_bf16 v[68:71], v[96:99], v[68:71], v[84:87]
	v_mfma_f32_16x16x32_bf16 v[72:75], v[96:99], v[72:75], v[88:91]
	v_mfma_f32_16x16x32_bf16 v[76:79], v[96:99], v[76:79], v[92:95]
	v_mfma_f32_16x16x32_bf16 v[32:35], v[64:67], v[32:35], v[48:51]
	s_nop 2
	v_cvt_pk_bf16_f32 v48, v140, v141
	v_cvt_pk_bf16_f32 v49, v142, v143
	v_cvt_pk_bf16_f32 v50, v136, v137
	v_cvt_pk_bf16_f32 v51, v138, v139
	v_mfma_f32_16x16x32_bf16 v[52:55], v[80:83], v[52:55], v[68:71]
	v_mfma_f32_16x16x32_bf16 v[56:59], v[80:83], v[56:59], v[72:75]
	v_mfma_f32_16x16x32_bf16 v[60:63], v[80:83], v[60:63], v[76:79]
	v_mfma_f32_16x16x32_bf16 v[36:39], v[64:67], v[36:39], v[52:55]
	v_mfma_f32_16x16x32_bf16 v[40:43], v[64:67], v[40:43], v[56:59]
	v_mfma_f32_16x16x32_bf16 v[44:47], v[64:67], v[44:47], v[60:63]
	v_mfma_f32_16x16x32_bf16 v[16:19], v[48:51], v[16:19], v[32:35]
	s_nop 2
	v_cvt_pk_bf16_f32 v32, v132, v133
	v_cvt_pk_bf16_f32 v33, v134, v135
	v_cvt_pk_bf16_f32 v34, v230, v231
	v_cvt_pk_bf16_f32 v35, v232, v221
	v_mfma_f32_16x16x32_bf16 v[20:23], v[48:51], v[20:23], v[36:39]
	v_mfma_f32_16x16x32_bf16 v[24:27], v[48:51], v[24:27], v[40:43]
	v_mfma_f32_16x16x32_bf16 v[28:31], v[48:51], v[28:31], v[44:47]
	v_mfma_f32_16x16x32_bf16 v[4:7], v[32:35], v[4:7], v[16:19]
	s_nop 2
	v_add_f32_e32 v16, v230, v204
	v_add_f32_e32 v16, v231, v16
	v_add_f32_e32 v16, v232, v16
	v_mfma_f32_16x16x32_bf16 v[8:11], v[32:35], v[8:11], v[20:23]
	v_add_f32_e32 v16, v221, v16
	v_mfma_f32_16x16x32_bf16 v[12:15], v[32:35], v[12:15], v[24:27]
	v_mfma_f32_16x16x32_bf16 v[0:3], v[32:35], v[0:3], v[28:31]
	ds_bpermute_b32 v17, v220, v16
	s_waitcnt lgkmcnt(0)
; __device__ __forceinline__ unsigned short f2bf_rne(float f) { unsigned u = __float_as_uint(f); return (unsigned short)((u + 0x7fffu + ((u >> 16) & 1u)) >> 16); }
; #define LAS __attribute__((address_space(3)))
; __device__ __forceinline__ void attn_unit(int u, const bf16_t* KB, const bf16_t* VT, const bf16_t* QU, bf16_t* OB, const LAS float* rpb_l, LAS unsigned char* ot, const LAS unsigned char* ckl, const LAS unsigned char* cvl, int lane_) {
;     ...
;     l += __shfl_xor(l, 16); l += __shfl_xor(l, 32);
;     const float inv = 1.0f / l;
;     asm volatile("" ::: "memory");
; #pragma unroll
;     for (int e = 0; e < 4; ++e) { const float il = __shfl(inv, 4 * fq + e);
; #pragma unroll
;         for (int dt = 0; dt < 4; ++dt) *(LAS unsigned short*)(ot + (4 * fq + e) * 128 + (dt * 16 + fr) * 2) = pg8::f2bf_rne(o[dt][e] * il); }
;     asm volatile("" ::: "memory");
; #pragma unroll
;     for (int k = 0; k < 2; ++k) { const int p = lane + 64 * k, q = p >> 3, dc = p & 7;
;         const u32x4 w = *(const LAS u32x4*)(ot + q * 128 + dc * 16);
;         *(u32x4*)(OB + (size_t)(qrow0 + q) * 1024 + h * 64 + dc * 8) = w; }
;     asm volatile("" ::: "memory");
	v_add_f32_e32 v16, v16, v17
	ds_bpermute_b32 v17, v202, v16
	s_waitcnt lgkmcnt(0)
	v_add_f32_e32 v16, v16, v17
	v_div_scale_f32 v17, s[4:5], v16, v16, 1.0
	v_rcp_f32_e32 v18, v17
	v_div_scale_f32 v19, vcc, 1.0, v16, 1.0
	s_lshl_b32 s4, s10, 1
	v_fma_f32 v20, -v17, v18, 1.0
	v_fmac_f32_e32 v18, v20, v18
	v_mul_f32_e32 v20, v19, v18
	v_fma_f32 v21, -v17, v20, v19
	v_fmac_f32_e32 v20, v21, v18
	v_fma_f32 v17, -v17, v20, v19
	v_div_fmas_f32 v17, v17, v18, v20
	v_div_fixup_f32 v16, v17, v16, 1.0
	ds_bpermute_b32 v17, v226, v16
	v_lshl_add_u32 v18, v216, 1, s44
	v_lshl_add_u32 v19, v217, 9, v18
	s_add_u32 s4, s42, s4
	s_addc_u32 s5, s43, 0
	s_waitcnt lgkmcnt(0)
	v_mul_f32_e32 v4, v4, v17
	v_mul_f32_e32 v8, v8, v17
	v_mul_f32_e32 v12, v12, v17
	v_bfe_u32 v20, v4, 16, 1
	v_bfe_u32 v21, v8, 16, 1
	v_bfe_u32 v22, v12, 16, 1
	v_add3_u32 v4, v4, v20, s65
	v_add3_u32 v8, v8, v21, s65
	v_add3_u32 v12, v12, v22, s65
	ds_write_b16_d16_hi v19, v4
	ds_write_b16_d16_hi v19, v8 offset:32
	ds_write_b16_d16_hi v19, v12 offset:64
	v_or_b32_e32 v4, 1, v224
	v_and_or_b32 v8, v4, 61, v225
	v_lshlrev_b32_e32 v8, 2, v8
	ds_bpermute_b32 v8, v8, v16
	v_mul_f32_e32 v0, v0, v17
	v_bfe_u32 v12, v0, 16, 1
	v_add3_u32 v0, v0, v12, s65
	ds_write_b16_d16_hi v19, v0 offset:96
	v_lshl_add_u32 v0, v4, 7, v18
	s_waitcnt lgkmcnt(1)
	v_mul_f32_e32 v4, v5, v8
	v_bfe_u32 v5, v4, 16, 1
	v_add3_u32 v4, v4, v5, s65
	ds_write_b16_d16_hi v0, v4
	v_mul_f32_e32 v4, v9, v8
	v_bfe_u32 v5, v4, 16, 1
	v_add3_u32 v4, v4, v5, s65
	ds_write_b16_d16_hi v0, v4 offset:32
	v_mul_f32_e32 v4, v13, v8
	v_bfe_u32 v5, v4, 16, 1
	v_add3_u32 v4, v4, v5, s65
	ds_write_b16_d16_hi v0, v4 offset:64
	v_or_b32_e32 v4, 2, v224
	v_and_or_b32 v5, v4, 62, v225
	v_lshlrev_b32_e32 v5, 2, v5
	ds_bpermute_b32 v5, v5, v16
	v_mul_f32_e32 v1, v1, v8
	v_bfe_u32 v8, v1, 16, 1
	v_add3_u32 v1, v1, v8, s65
	ds_write_b16_d16_hi v0, v1 offset:96
	s_waitcnt lgkmcnt(1)
	v_mul_f32_e32 v1, v6, v5
	v_lshl_add_u32 v0, v4, 7, v18
	v_bfe_u32 v4, v1, 16, 1
	v_add3_u32 v1, v1, v4, s65
	ds_write_b16_d16_hi v0, v1
	v_mul_f32_e32 v1, v10, v5
	v_bfe_u32 v4, v1, 16, 1
	v_add3_u32 v1, v1, v4, s65
	ds_write_b16_d16_hi v0, v1 offset:32
	v_mul_f32_e32 v1, v14, v5
	v_bfe_u32 v4, v1, 16, 1
	v_add3_u32 v1, v1, v4, s65
	ds_write_b16_d16_hi v0, v1 offset:64
	v_mul_f32_e32 v1, v2, v5
	v_or_b32_e32 v2, 3, v224
	v_and_or_b32 v4, v2, 63, v225
	v_lshlrev_b32_e32 v4, 2, v4
	ds_bpermute_b32 v4, v4, v16
	v_bfe_u32 v5, v1, 16, 1
	v_add3_u32 v1, v1, v5, s65
	ds_write_b16_d16_hi v0, v1 offset:96
	v_lshl_add_u32 v0, v2, 7, v18
	s_waitcnt lgkmcnt(1)
	v_mul_f32_e32 v1, v7, v4
	v_bfe_u32 v2, v1, 16, 1
	v_add3_u32 v1, v1, v2, s65
	ds_write_b16_d16_hi v0, v1
	v_mul_f32_e32 v1, v11, v4
	v_bfe_u32 v2, v1, 16, 1
	v_add3_u32 v1, v1, v2, s65
	ds_write_b16_d16_hi v0, v1 offset:32
	v_mul_f32_e32 v1, v15, v4
	v_bfe_u32 v2, v1, 16, 1
	v_add3_u32 v1, v1, v2, s65
	ds_write_b16_d16_hi v0, v1 offset:64
	v_mul_f32_e32 v1, v3, v4
	v_bfe_u32 v2, v1, 16, 1
	v_add3_u32 v1, v1, v2, s65
	ds_write_b16_d16_hi v0, v1 offset:96
	v_lshlrev_b32_e32 v0, 4, v215
	v_and_b32_e32 v202, 0x70, v0
	v_add_u32_e32 v6, s44, v202
	v_ashrrev_i32_e32 v4, 3, v215
	v_lshl_add_u32 v0, v4, 7, v6
	v_add_u32_e32 v4, s36, v4
	v_ashrrev_i32_e32 v5, 31, v4
	v_lshl_add_u64 v[8:9], s[4:5], 0, v[202:203]
	ds_read_b128 v[0:3], v0
	v_lshlrev_b64 v[4:5], 11, v[4:5]
	v_lshl_add_u64 v[10:11], v[8:9], 0, v[4:5]
	v_add_u32_e32 v4, 64, v215
	v_ashrrev_i32_e32 v12, 3, v4
	v_lshl_add_u32 v4, v12, 7, v6
	ds_read_b128 v[4:7], v4
	s_waitcnt lgkmcnt(1)
	global_store_dwordx4 v[10:11], v[0:3], off
	s_nop 1
	v_add_u32_e32 v0, s36, v12
	v_ashrrev_i32_e32 v1, 31, v0
	v_lshlrev_b64 v[0:1], 11, v[0:1]
	v_lshl_add_u64 v[0:1], v[8:9], 0, v[0:1]
	s_waitcnt lgkmcnt(0)
	global_store_dwordx4 v[0:1], v[4:7], off

; #define LAS __attribute__((address_space(3)))
; __device__ __forceinline__ void attn_unit(int u, const bf16_t* KB, const bf16_t* VT, const bf16_t* QU, bf16_t* OB, const LAS float* rpb_l, LAS unsigned char* ot, const LAS unsigned char* ckl, const LAS unsigned char* cvl, int lane_) {
;     ...
;         const int c = 16 * cb + fr, cs = min(max(c - 8, 0), 48); const LAS float* rp = rpb_l + h * 465 + (rs - r + 7) * 31;
; #pragma unroll
;         for (int t = 0; t < 2; ++t)
; #pragma unroll
;             for (int e = 0; e < 4; ++e) { const int kc = c0 + 8 * fq + 4 * t + e; const bool valid = (kc >= cs) && (kc < cs + 16); const int dc = min(max(kc - c + 15, 0), 30);
;                 float bz[8];
; #pragma unroll
;                 for (int i = 0; i < 8; ++i) bz[i] = rp[i * 31 + dc];
;                 asm volatile("" : "+v"(bz[0]), "+v"(bz[1]), "+v"(bz[2]), "+v"(bz[3]), "+v"(bz[4]), "+v"(bz[5]), "+v"(bz[6]), "+v"(bz[7]));
; #pragma unroll
;                 for (int i = 0; i < 8; ++i) st[i][t][e] = valid ? st[i][t][e] + bz[i] : NEG; }
.Lat1_p2:
	v_or_b32_e32 v200, s35, v210
	v_add_u32_e32 v224, s17, v214
	v_sub_u32_e64 v215, v200, 8 clamp
	v_sub_u32_e32 v214, v224, v200
	v_min_u32_e32 v222, 48, v215
	v_subrev_u32_e32 v215, s34, v216
	v_max_i32_e32 v214, -15, v214
	v_mul_lo_u32 v215, v215, s56
	v_add_u32_e32 v214, 15, v214
	v_add_u32_e32 v223, s42, v215
	v_min_u32_e32 v214, 30, v214
	v_lshl_add_u32 v216, v214, 2, v223
	v_add_u32_e32 v220, 0x400, v216
	ds_read2_b32 v[214:215], v220 offset0:147 offset1:178
	ds_read2_b32 v[216:217], v216 offset0:217 offset1:248
	ds_read2_b32 v[218:219], v220 offset0:23 offset1:54
	ds_read2_b32 v[220:221], v220 offset0:85 offset1:116
	v_add_u32_e32 v225, 16, v222
	v_cmp_lt_i32_e32 vcc, v224, v225
	v_cmp_ge_i32_e64 s[6:7], v224, v222
	s_waitcnt lgkmcnt(0)
	s_nop 0
	v_add_f32_e32 v168, v168, v216
	s_and_b64 vcc, s[6:7], vcc
	v_cndmask_b32_e32 v226, v208, v168, vcc
	v_add_f32_e32 v168, v172, v217
	v_cndmask_b32_e32 v227, v208, v168, vcc
	v_add_f32_e32 v168, v176, v218
	v_cndmask_b32_e32 v228, v208, v168, vcc
	v_add_f32_e32 v168, v180, v219
	v_cndmask_b32_e32 v229, v208, v168, vcc
	v_add_f32_e32 v168, v184, v220
	v_or_b32_e32 v184, 1, v224
	v_cndmask_b32_e32 v180, v208, v168, vcc
	v_add_f32_e32 v168, v188, v221
	v_sub_u32_e32 v188, v184, v200
	v_max_i32_e32 v188, -15, v188
	v_add_u32_e32 v188, 15, v188
	v_min_u32_e32 v188, 30, v188
	v_lshl_add_u32 v188, v188, 2, v223
	v_cndmask_b32_e32 v176, v208, v168, vcc
	v_add_f32_e32 v168, v192, v214
	v_add_u32_e32 v192, 0x400, v188
	v_cndmask_b32_e32 v172, v208, v168, vcc
	v_add_f32_e32 v168, v196, v215
	ds_read2_b32 v[214:215], v192 offset0:23 offset1:54
	ds_read2_b32 v[216:217], v192 offset0:85 offset1:116
	ds_read2_b32 v[218:219], v192 offset0:147 offset1:178
	ds_read2_b32 v[220:221], v188 offset0:217 offset1:248
	v_cndmask_b32_e32 v168, v208, v168, vcc
	v_cmp_lt_i32_e32 vcc, v184, v225
	v_cmp_ge_i32_e64 s[6:7], v184, v222
	s_waitcnt lgkmcnt(3)
	v_mov_b32_e32 v184, v214
	s_waitcnt lgkmcnt(2)
	v_mov_b32_e32 v188, v216
	s_waitcnt lgkmcnt(1)
	v_mov_b32_e32 v192, v218
	s_waitcnt lgkmcnt(0)
	v_mov_b32_e32 v196, v221
	s_and_b64 vcc, s[6:7], vcc
	v_add_f32_e32 v169, v169, v220
	v_cndmask_b32_e32 v214, v208, v169, vcc
	v_add_f32_e32 v169, v173, v196
	v_or_b32_e32 v173, 2, v224
	v_cndmask_b32_e32 v216, v208, v169, vcc
	v_add_f32_e32 v169, v177, v184
	v_sub_u32_e32 v184, v173, v200
	v_max_i32_e32 v184, -15, v184
	v_cndmask_b32_e32 v218, v208, v169, vcc
	v_add_f32_e32 v169, v181, v215
	v_add_u32_e32 v184, 15, v184
	v_cndmask_b32_e32 v215, v208, v169, vcc
	v_add_f32_e32 v169, v185, v188
	v_min_u32_e32 v184, 30, v184
	v_cndmask_b32_e32 v220, v208, v169, vcc
	v_add_f32_e32 v169, v189, v217
	v_lshl_add_u32 v184, v184, 2, v223
	v_cndmask_b32_e32 v181, v208, v169, vcc
	v_add_f32_e32 v169, v193, v192
	v_add_u32_e32 v196, 0x400, v184
	v_cndmask_b32_e32 v177, v208, v169, vcc
	v_add_f32_e32 v169, v197, v219
	ds_read2_b32 v[184:185], v184 offset0:217 offset1:248
	ds_read2_b32 v[188:189], v196 offset0:23 offset1:54
	ds_read2_b32 v[192:193], v196 offset0:85 offset1:116
	ds_read2_b32 v[196:197], v196 offset0:147 offset1:178
	v_cndmask_b32_e32 v169, v208, v169, vcc
	v_cmp_lt_i32_e32 vcc, v173, v225
	v_cmp_ge_i32_e64 s[6:7], v173, v222
	s_waitcnt lgkmcnt(3)
	v_mov_b32_e32 v173, v184
	s_waitcnt lgkmcnt(2)
	v_mov_b32_e32 v184, v188
	s_waitcnt lgkmcnt(1)
	v_mov_b32_e32 v188, v192
	s_waitcnt lgkmcnt(0)
	v_mov_b32_e32 v192, v196
	s_and_b64 vcc, s[6:7], vcc
	v_add_f32_e32 v170, v170, v173
	v_or_b32_e32 v173, 3, v224
	v_cndmask_b32_e32 v217, v208, v170, vcc
	v_add_f32_e32 v170, v174, v185
	v_sub_u32_e32 v174, v173, v200
	v_cndmask_b32_e32 v219, v208, v170, vcc
	v_add_f32_e32 v170, v178, v184
	v_max_i32_e32 v174, -15, v174
	v_cndmask_b32_e32 v221, v208, v170, vcc
	v_add_f32_e32 v170, v182, v189
	v_add_u32_e32 v174, 15, v174
	v_cndmask_b32_e32 v230, v208, v170, vcc
	v_add_f32_e32 v170, v186, v188
	v_min_u32_e32 v174, 30, v174
	v_cndmask_b32_e32 v186, v208, v170, vcc
	v_add_f32_e32 v170, v190, v193
	v_lshl_add_u32 v174, v174, 2, v223
	v_cndmask_b32_e32 v190, v208, v170, vcc
	v_add_f32_e32 v170, v194, v192
	v_add_u32_e32 v178, 0x400, v174
	v_cndmask_b32_e32 v194, v208, v170, vcc
	v_add_f32_e32 v170, v198, v197
	ds_read2_b32 v[184:185], v178 offset0:85 offset1:116
	ds_read2_b32 v[188:189], v174 offset0:217 offset1:248
	ds_read2_b32 v[192:193], v178 offset0:147 offset1:178
	ds_read2_b32 v[196:197], v178 offset0:23 offset1:54
	v_cndmask_b32_e32 v170, v208, v170, vcc
	v_cmp_lt_i32_e32 vcc, v173, v225
	v_cmp_ge_i32_e64 s[6:7], v173, v222
	s_waitcnt lgkmcnt(3)
	v_mov_b32_e32 v173, v185
	s_waitcnt lgkmcnt(2)
	v_mov_b32_e32 v174, v188
	s_waitcnt lgkmcnt(1)
	v_mov_b32_e32 v178, v193
	s_waitcnt lgkmcnt(0)
	v_mov_b32_e32 v182, v196
	s_and_b64 vcc, s[6:7], vcc
	v_add_f32_e32 v171, v171, v174
	v_add_f32_e32 v174, v175, v189
	v_add_f32_e32 v173, v191, v173
	v_cndmask_b32_e32 v188, v208, v174, vcc
	v_add_f32_e32 v174, v179, v182
	v_cndmask_b32_e32 v191, v208, v173, vcc
	v_add_f32_e32 v173, v195, v192
	v_cndmask_b32_e32 v189, v208, v174, vcc
	v_add_f32_e32 v174, v183, v197
	v_cndmask_b32_e32 v192, v208, v173, vcc
	v_add_f32_e32 v173, v199, v178
	v_cndmask_b32_e32 v193, v208, v174, vcc
	v_add_f32_e32 v174, v187, v184
	v_cndmask_b32_e32 v195, v208, v173, vcc
	v_or_b32_e32 v173, 4, v224
	v_cndmask_b32_e32 v187, v208, v174, vcc
	v_sub_u32_e32 v174, v173, v200
	v_max_i32_e32 v174, -15, v174
	v_add_u32_e32 v174, 15, v174
	v_min_u32_e32 v174, 30, v174
	v_lshl_add_u32 v178, v174, 2, v223
	v_add_u32_e32 v184, 0x400, v178
	ds_read2_b32 v[174:175], v184 offset0:147 offset1:178
	ds_read2_b32 v[178:179], v178 offset0:217 offset1:248
	ds_read2_b32 v[182:183], v184 offset0:23 offset1:54
	ds_read2_b32 v[184:185], v184 offset0:85 offset1:116
	v_cndmask_b32_e32 v171, v208, v171, vcc
	v_cmp_lt_i32_e32 vcc, v173, v225
	v_cmp_ge_i32_e64 s[6:7], v173, v222
	s_waitcnt lgkmcnt(3)
; __device__ __forceinline__ void attn_unit(int u, const bf16_t* KB, const bf16_t* VT, const bf16_t* QU, bf16_t* OB, const LAS float* rpb_l, LAS unsigned char* ot, const LAS unsigned char* ckl, const LAS unsigned char* cvl, int lane_) {
;     ...
;             for (int e = 0; e < 4; ++e) { const int kc = c0 + 8 * fq + 4 * t + e; const bool valid = (kc >= cs) && (kc < cs + 16); const int dc = min(max(kc - c + 15, 0), 30);
;                 float bz[8];
; #pragma unroll
;                 for (int i = 0; i < 8; ++i) bz[i] = rp[i * 31 + dc];
;                 asm volatile("" : "+v"(bz[0]), "+v"(bz[1]), "+v"(bz[2]), "+v"(bz[3]), "+v"(bz[4]), "+v"(bz[5]), "+v"(bz[6]), "+v"(bz[7]));
; #pragma unroll
;                 for (int i = 0; i < 8; ++i) st[i][t][e] = valid ? st[i][t][e] + bz[i] : NEG; }
; #pragma unroll
;         for (int g = 0; g < 8; ++g)
; #pragma unroll
;             for (int t = 0; t < 2; ++t) m = fmaxf(m, fmaxf(fmaxf(st[g][t][0], st[g][t][1]), fmaxf(st[g][t][2], st[g][t][3])));
;         m = fmaxf(m, __shfl_xor(m, 16)); m = fmaxf(m, __shfl_xor(m, 32));
	v_mov_b32_e32 v173, v174
	s_waitcnt lgkmcnt(2)
	v_mov_b32_e32 v174, v179
	s_waitcnt lgkmcnt(1)
	v_mov_b32_e32 v179, v183
	s_waitcnt lgkmcnt(0)
	v_mov_b32_e32 v183, v185
	s_and_b64 vcc, s[6:7], vcc
	v_add_f32_e32 v136, v136, v178
	v_cndmask_b32_e32 v198, v208, v136, vcc
	v_add_f32_e32 v136, v140, v174
	v_cndmask_b32_e32 v199, v208, v136, vcc
	v_add_f32_e32 v136, v144, v182
	v_cndmask_b32_e32 v231, v208, v136, vcc
	v_add_f32_e32 v136, v148, v179
	v_cndmask_b32_e32 v232, v208, v136, vcc
	v_add_f32_e32 v136, v152, v184
	v_cndmask_b32_e32 v152, v208, v136, vcc
	v_add_f32_e32 v136, v156, v183
	v_cndmask_b32_e32 v156, v208, v136, vcc
	v_add_f32_e32 v136, v160, v173
	v_cndmask_b32_e32 v160, v208, v136, vcc
	v_add_f32_e32 v136, v164, v175
	v_cndmask_b32_e32 v164, v208, v136, vcc
	v_or_b32_e32 v136, 5, v224
	v_sub_u32_e32 v140, v136, v200
	v_max_i32_e32 v140, -15, v140
	v_add_u32_e32 v140, 15, v140
	v_min_u32_e32 v140, 30, v140
	v_lshl_add_u32 v140, v140, 2, v223
	v_add_u32_e32 v144, 0x400, v140
	ds_read2_b32 v[174:175], v144 offset0:23 offset1:54
	ds_read2_b32 v[178:179], v144 offset0:85 offset1:116
	ds_read2_b32 v[182:183], v144 offset0:147 offset1:178
	ds_read2_b32 v[184:185], v140 offset0:217 offset1:248
	v_cmp_lt_i32_e32 vcc, v136, v225
	v_cmp_ge_i32_e64 s[6:7], v136, v222
	s_waitcnt lgkmcnt(3)
	v_mov_b32_e32 v136, v174
	s_waitcnt lgkmcnt(2)
	v_mov_b32_e32 v140, v178
	s_waitcnt lgkmcnt(1)
	v_mov_b32_e32 v144, v182
	s_waitcnt lgkmcnt(0)
	v_mov_b32_e32 v148, v185
	s_and_b64 vcc, s[6:7], vcc
	v_add_f32_e32 v136, v145, v136
	v_cndmask_b32_e32 v182, v208, v136, vcc
	v_add_f32_e32 v136, v149, v175
	v_cndmask_b32_e32 v175, v208, v136, vcc
	v_add_f32_e32 v136, v153, v140
	v_cndmask_b32_e32 v153, v208, v136, vcc
	v_add_f32_e32 v136, v157, v179
	v_cndmask_b32_e32 v157, v208, v136, vcc
	v_add_f32_e32 v136, v161, v144
	v_cndmask_b32_e32 v161, v208, v136, vcc
	v_add_f32_e32 v136, v165, v183
	v_or_b32_e32 v173, 6, v224
	v_cndmask_b32_e32 v165, v208, v136, vcc
	v_sub_u32_e32 v136, v173, v200
	v_max_i32_e32 v136, -15, v136
	v_add_u32_e32 v136, 15, v136
	v_min_u32_e32 v136, 30, v136
	v_add_f32_e32 v137, v137, v184
	v_lshl_add_u32 v136, v136, 2, v223
	v_cndmask_b32_e32 v174, v208, v137, vcc
	v_add_f32_e32 v137, v141, v148
	v_add_u32_e32 v148, 0x400, v136
	v_cndmask_b32_e32 v178, v208, v137, vcc
	ds_read2_b32 v[136:137], v136 offset0:217 offset1:248
	ds_read2_b32 v[140:141], v148 offset0:23 offset1:54
	ds_read2_b32 v[144:145], v148 offset0:85 offset1:116
	ds_read2_b32 v[148:149], v148 offset0:147 offset1:178
	v_cmp_lt_i32_e32 vcc, v173, v225
	v_cmp_ge_i32_e64 s[6:7], v173, v222
	s_waitcnt lgkmcnt(0)
	s_nop 0
	v_add_f32_e32 v136, v138, v136
	s_and_b64 vcc, s[6:7], vcc
	v_cndmask_b32_e32 v138, v208, v136, vcc
	v_add_f32_e32 v136, v142, v137
	v_cndmask_b32_e32 v142, v208, v136, vcc
	v_add_f32_e32 v136, v146, v140
	v_cndmask_b32_e32 v146, v208, v136, vcc
	v_add_f32_e32 v136, v150, v141
	v_cndmask_b32_e32 v150, v208, v136, vcc
	v_add_f32_e32 v136, v154, v144
	v_cndmask_b32_e32 v154, v208, v136, vcc
	v_add_f32_e32 v136, v158, v145
	v_cndmask_b32_e32 v158, v208, v136, vcc
	v_add_f32_e32 v136, v162, v148
	v_cndmask_b32_e32 v162, v208, v136, vcc
	v_add_f32_e32 v136, v166, v149
	v_or_b32_e32 v173, 7, v224
	v_cndmask_b32_e32 v166, v208, v136, vcc
	v_sub_u32_e32 v136, v173, v200
	v_max_i32_e32 v136, -15, v136
	v_add_u32_e32 v136, 15, v136
	v_min_u32_e32 v136, 30, v136
	v_lshl_add_u32 v140, v136, 2, v223
	v_add_u32_e32 v148, 0x400, v140
	ds_read2_b32 v[136:137], v148 offset0:85 offset1:116
	ds_read2_b32 v[140:141], v140 offset0:217 offset1:248
	ds_read2_b32 v[144:145], v148 offset0:147 offset1:178
	ds_read2_b32 v[148:149], v148 offset0:23 offset1:54
	v_cmp_lt_i32_e32 vcc, v173, v225
	v_cmp_ge_i32_e64 s[6:7], v173, v222
	s_waitcnt lgkmcnt(0)
	s_nop 0
	v_add_f32_e32 v139, v139, v140
	s_and_b64 vcc, s[6:7], vcc
	v_cndmask_b32_e32 v139, v208, v139, vcc
	v_add_f32_e32 v140, v143, v141
	v_add_f32_e32 v141, v147, v148
	v_max_f32_e32 v147, v217, v171
	v_max_f32_e32 v148, v138, v139
	v_cndmask_b32_e32 v140, v208, v140, vcc
	v_max3_f32 v147, v226, v214, v147
	v_max3_f32 v148, v198, v174, v148
	v_add_f32_e32 v143, v151, v149
	v_max3_f32 v147, v147, s57, v148
	v_max_f32_e32 v148, v219, v188
	v_max_f32_e32 v149, v142, v140
	v_cndmask_b32_e32 v141, v208, v141, vcc
	v_max3_f32 v148, v227, v216, v148
	v_max3_f32 v149, v199, v178, v149
	v_max3_f32 v147, v147, v148, v149
	v_max_f32_e32 v148, v221, v189
	v_max_f32_e32 v149, v146, v141
	v_cndmask_b32_e32 v143, v208, v143, vcc
	v_max3_f32 v148, v228, v218, v148
	v_max3_f32 v149, v231, v182, v149
	v_add_f32_e32 v136, v155, v136
	v_max3_f32 v147, v147, v148, v149
	v_max_f32_e32 v148, v230, v193
	v_max_f32_e32 v149, v150, v143
	v_cndmask_b32_e32 v136, v208, v136, vcc
	v_max3_f32 v148, v229, v215, v148
	v_max3_f32 v149, v232, v175, v149
	v_add_f32_e32 v137, v159, v137
	v_max3_f32 v147, v147, v148, v149
	v_max_f32_e32 v148, v186, v187
	v_max_f32_e32 v149, v154, v136
	v_cndmask_b32_e32 v137, v208, v137, vcc
	v_max3_f32 v148, v180, v220, v148
	v_max3_f32 v149, v152, v153, v149
	v_add_f32_e32 v144, v163, v144
	v_max3_f32 v147, v147, v148, v149
	v_max_f32_e32 v148, v190, v191
	v_max_f32_e32 v149, v158, v137
	v_cndmask_b32_e32 v144, v208, v144, vcc
	v_max3_f32 v148, v176, v181, v148
	v_max3_f32 v149, v156, v157, v149
	v_add_f32_e32 v145, v167, v145
	v_max3_f32 v147, v147, v148, v149
	v_max_f32_e32 v148, v194, v192
	v_max_f32_e32 v149, v162, v144
	v_cndmask_b32_e32 v145, v208, v145, vcc
	v_max3_f32 v148, v172, v177, v148
	v_max3_f32 v149, v160, v161, v149
	v_max3_f32 v147, v147, v148, v149
	v_max_f32_e32 v148, v170, v195
	v_max_f32_e32 v149, v166, v145
	v_max3_f32 v148, v168, v169, v148
	v_max3_f32 v149, v164, v165, v149
	v_cmp_lt_i32_e32 vcc, v204, v203
	v_max3_f32 v147, v147, v148, v149
	s_nop 0
	v_cndmask_b32_e32 v148, v202, v204, vcc
	v_lshlrev_b32_e32 v196, 2, v148
	ds_bpermute_b32 v148, v196, v147
	s_waitcnt lgkmcnt(0)
; __device__ __forceinline__ unsigned cvtpk_s(float lo, float hi) { f32x2_t v = {lo, hi}; bf16x2_t b = __builtin_convertvector(v, bf16x2_t); return __builtin_bit_cast(unsigned, b); }
; #define ATTN_SB() __builtin_amdgcn_sched_barrier(0)
; __device__ __forceinline__ void attn_unit(int u, const bf16_t* KB, const bf16_t* VT, const bf16_t* QU, bf16_t* OB, const LAS float* rpb_l, LAS unsigned char* ot, const LAS unsigned char* ckl, const LAS unsigned char* cvl, int lane_) {
;     ...
;         m = fmaxf(m, __shfl_xor(m, 16)); m = fmaxf(m, __shfl_xor(m, 32));
; #pragma unroll
;         for (int g = 0; g < 8; ++g)
; #pragma unroll
;             for (int t = 0; t < 2; ++t)
; #pragma unroll
;                 for (int e = 0; e < 4; ++e) { const float p = __builtin_amdgcn_exp2f(st[g][t][e] - m); st[g][t][e] = p; l += p; }
;         ATTN_SB();
; #pragma unroll
;         for (int i = 0; i < 8; ++i) {
;             u32x4 pw; pw.x = cvtpk_s(st[i][0][0], st[i][0][1]); pw.y = cvtpk_s(st[i][0][2], st[i][0][3]); pw.z = cvtpk_s(st[i][1][0], st[i][1][1]); pw.w = cvtpk_s(st[i][1][2], st[i][1][3]);
	v_max_f32_e32 v148, v148, v148
	v_max_f32_e32 v147, v147, v148
	v_xor_b32_e32 v148, 32, v202
	v_cmp_lt_i32_e32 vcc, v148, v203
	s_nop 1
	v_cndmask_b32_e32 v148, v202, v148, vcc
	v_lshlrev_b32_e32 v197, 2, v148
	ds_bpermute_b32 v148, v197, v147
	s_waitcnt lgkmcnt(0)
	v_max_f32_e32 v148, v148, v148
	v_max_f32_e32 v173, v147, v148
	v_sub_f32_e32 v147, v226, v173
	v_exp_f32_e32 v147, v147
	v_sub_f32_e32 v149, v214, v173
	v_exp_f32_e32 v149, v149
	v_sub_f32_e32 v151, v217, v173
	v_exp_f32_e32 v151, v151
	v_sub_f32_e32 v155, v171, v173
	v_exp_f32_e32 v155, v155
	v_sub_f32_e32 v159, v198, v173
	v_add_f32_e32 v148, 0, v147
	v_exp_f32_e32 v159, v159
	v_sub_f32_e32 v163, v174, v173
	v_add_f32_e32 v148, v149, v148
	v_exp_f32_e32 v163, v163
	v_add_f32_e32 v148, v151, v148
	v_sub_f32_e32 v138, v138, v173
	v_add_f32_e32 v148, v155, v148
	v_exp_f32_e32 v167, v138
	v_sub_f32_e32 v138, v139, v173
	v_add_f32_e32 v148, v159, v148
	v_exp_f32_e32 v139, v138
	v_sub_f32_e32 v138, v227, v173
	v_exp_f32_e32 v171, v138
	v_add_f32_e32 v138, v163, v148
	v_sub_f32_e32 v148, v216, v173
	v_exp_f32_e32 v148, v148
	v_sub_f32_e32 v174, v219, v173
	v_add_f32_e32 v138, v167, v138
	v_exp_f32_e32 v174, v174
	v_sub_f32_e32 v179, v188, v173
	v_add_f32_e32 v138, v139, v138
	v_exp_f32_e32 v179, v179
	v_sub_f32_e32 v183, v199, v173
	v_add_f32_e32 v138, v171, v138
	v_exp_f32_e32 v183, v183
	v_sub_f32_e32 v178, v178, v173
	v_add_f32_e32 v138, v148, v138
	v_exp_f32_e32 v178, v178
	v_sub_f32_e32 v142, v142, v173
	v_add_f32_e32 v138, v174, v138
	v_exp_f32_e32 v142, v142
	v_sub_f32_e32 v140, v140, v173
	v_add_f32_e32 v138, v179, v138
	v_exp_f32_e32 v140, v140
	v_sub_f32_e32 v184, v228, v173
	v_add_f32_e32 v138, v183, v138
	v_exp_f32_e32 v184, v184
	v_sub_f32_e32 v185, v218, v173
	v_add_f32_e32 v138, v178, v138
	v_exp_f32_e32 v185, v185
	v_sub_f32_e32 v188, v221, v173
	v_add_f32_e32 v138, v142, v138
	v_exp_f32_e32 v188, v188
	v_sub_f32_e32 v189, v189, v173
	v_add_f32_e32 v138, v140, v138
	v_exp_f32_e32 v189, v189
	v_sub_f32_e32 v198, v231, v173
	v_add_f32_e32 v138, v184, v138
	v_exp_f32_e32 v198, v198
	v_sub_f32_e32 v182, v182, v173
	v_add_f32_e32 v138, v185, v138
	v_exp_f32_e32 v182, v182
	v_sub_f32_e32 v146, v146, v173
	v_add_f32_e32 v138, v188, v138
	v_exp_f32_e32 v146, v146
	v_sub_f32_e32 v141, v141, v173
	v_add_f32_e32 v138, v189, v138
	v_exp_f32_e32 v141, v141
	v_sub_f32_e32 v199, v229, v173
	v_add_f32_e32 v138, v198, v138
	v_exp_f32_e32 v199, v199
	v_sub_f32_e32 v200, v215, v173
	v_add_f32_e32 v138, v182, v138
	v_exp_f32_e32 v200, v200
	v_sub_f32_e32 v214, v230, v173
	v_add_f32_e32 v138, v146, v138
	v_exp_f32_e32 v214, v214
	v_sub_f32_e32 v193, v193, v173
	v_add_f32_e32 v138, v141, v138
	v_exp_f32_e32 v193, v193
	v_sub_f32_e32 v215, v232, v173
	v_add_f32_e32 v138, v199, v138
	v_exp_f32_e32 v215, v215
	v_sub_f32_e32 v175, v175, v173
	v_add_f32_e32 v138, v200, v138
	v_exp_f32_e32 v175, v175
	v_sub_f32_e32 v150, v150, v173
	v_add_f32_e32 v138, v214, v138
	v_exp_f32_e32 v150, v150
	v_sub_f32_e32 v143, v143, v173
	v_add_f32_e32 v138, v193, v138
	v_exp_f32_e32 v143, v143
	v_sub_f32_e32 v180, v180, v173
	v_add_f32_e32 v138, v215, v138
	v_exp_f32_e32 v180, v180
	v_sub_f32_e32 v216, v220, v173
	v_add_f32_e32 v138, v175, v138
	v_exp_f32_e32 v216, v216
	v_sub_f32_e32 v186, v186, v173
	v_add_f32_e32 v138, v150, v138
	v_exp_f32_e32 v186, v186
	v_sub_f32_e32 v187, v187, v173
	v_add_f32_e32 v138, v143, v138
	v_exp_f32_e32 v187, v187
	v_sub_f32_e32 v152, v152, v173
	v_add_f32_e32 v138, v180, v138
	v_exp_f32_e32 v152, v152
	v_sub_f32_e32 v153, v153, v173
	v_add_f32_e32 v138, v216, v138
	v_exp_f32_e32 v153, v153
	v_add_f32_e32 v138, v186, v138
	v_sub_f32_e32 v154, v154, v173
	v_add_f32_e32 v138, v187, v138
	v_exp_f32_e32 v154, v154
	v_sub_f32_e32 v136, v136, v173
	v_add_f32_e32 v138, v152, v138
	v_exp_f32_e32 v217, v136
	v_sub_f32_e32 v136, v176, v173
	v_exp_f32_e32 v176, v136
	v_add_f32_e32 v136, v153, v138
	v_sub_f32_e32 v138, v181, v173
	v_exp_f32_e32 v181, v138
	v_sub_f32_e32 v138, v190, v173
	v_add_f32_e32 v136, v154, v136
	v_exp_f32_e32 v190, v138
	v_sub_f32_e32 v138, v191, v173
	v_add_f32_e32 v136, v217, v136
	v_exp_f32_e32 v191, v138
	v_sub_f32_e32 v138, v156, v173
	v_add_f32_e32 v136, v176, v136
	v_exp_f32_e32 v156, v138
	v_sub_f32_e32 v138, v157, v173
	v_add_f32_e32 v136, v181, v136
	v_exp_f32_e32 v157, v138
	v_sub_f32_e32 v138, v158, v173
	v_add_f32_e32 v136, v190, v136
	v_exp_f32_e32 v158, v138
	v_sub_f32_e32 v137, v137, v173
	v_add_f32_e32 v136, v191, v136
	v_exp_f32_e32 v218, v137
	v_sub_f32_e32 v137, v172, v173
	v_add_f32_e32 v136, v156, v136
	v_exp_f32_e32 v172, v137
	v_sub_f32_e32 v137, v177, v173
	v_add_f32_e32 v136, v157, v136
	v_exp_f32_e32 v177, v137
	v_sub_f32_e32 v137, v194, v173
	v_add_f32_e32 v136, v158, v136
	v_exp_f32_e32 v194, v137
	v_sub_f32_e32 v137, v192, v173
	v_add_f32_e32 v136, v218, v136
	v_exp_f32_e32 v192, v137
	v_sub_f32_e32 v137, v160, v173
	v_add_f32_e32 v136, v172, v136
	v_exp_f32_e32 v160, v137
	v_sub_f32_e32 v137, v161, v173
	v_add_f32_e32 v136, v177, v136
	v_exp_f32_e32 v161, v137
	v_sub_f32_e32 v137, v162, v173
	v_add_f32_e32 v136, v194, v136
	v_exp_f32_e32 v162, v137
	v_sub_f32_e32 v137, v144, v173
	v_add_f32_e32 v136, v192, v136
	v_exp_f32_e32 v144, v137
	v_sub_f32_e32 v137, v168, v173
	v_add_f32_e32 v136, v160, v136
	v_exp_f32_e32 v168, v137
	v_sub_f32_e32 v137, v169, v173
	v_add_f32_e32 v136, v161, v136
	v_exp_f32_e32 v169, v137
	v_sub_f32_e32 v137, v170, v173
	v_add_f32_e32 v136, v162, v136
	v_exp_f32_e32 v170, v137
	v_sub_f32_e32 v137, v195, v173
	v_add_f32_e32 v136, v144, v136
	v_exp_f32_e32 v195, v137
	v_sub_f32_e32 v137, v164, v173
	v_add_f32_e32 v136, v168, v136
	v_exp_f32_e32 v164, v137
	v_sub_f32_e32 v137, v165, v173
	v_exp_f32_e32 v165, v137
	v_sub_f32_e32 v137, v166, v173
	v_add_f32_e32 v136, v169, v136
	v_exp_f32_e32 v166, v137
	v_sub_f32_e32 v137, v145, v173
	v_add_f32_e32 v136, v170, v136
	v_exp_f32_e32 v145, v137
	v_add_f32_e32 v219, v195, v136
	v_cvt_pk_bf16_f32 v136, v147, v149
	v_cvt_pk_bf16_f32 v137, v151, v155
	v_cvt_pk_bf16_f32 v138, v159, v163
	v_cvt_pk_bf16_f32 v139, v167, v139
	s_waitcnt vmcnt(31)
; #define LAS __attribute__((address_space(3)))
; __device__ __forceinline__ unsigned cvtpk_s(float lo, float hi) { f32x2_t v = {lo, hi}; bf16x2_t b = __builtin_convertvector(v, bf16x2_t); return __builtin_bit_cast(unsigned, b); }
; #define MFMA16(a, b, c) __builtin_amdgcn_mfma_f32_16x16x32_bf16((a), (b), (c), 0, 0, 0)
; #define ATTN_SB() __builtin_amdgcn_sched_barrier(0)
; __device__ __forceinline__ void attn_unit(int u, const bf16_t* KB, const bf16_t* VT, const bf16_t* QU, bf16_t* OB, const LAS float* rpb_l, LAS unsigned char* ot, const LAS unsigned char* ckl, const LAS unsigned char* cvl, int lane_) {
;     ...
; #pragma unroll
;         for (int i = 0; i < 8; ++i) {
;             u32x4 pw; pw.x = cvtpk_s(st[i][0][0], st[i][0][1]); pw.y = cvtpk_s(st[i][0][2], st[i][0][3]); pw.z = cvtpk_s(st[i][1][0], st[i][1][1]); pw.w = cvtpk_s(st[i][1][2], st[i][1][3]);
;             const bf16x8 pa = __builtin_bit_cast(bf16x8, pw);
; #pragma unroll
;             for (int dt = 0; dt < 4; ++dt) o[dt] = MFMA16(pa, fb[i * 4 + dt], o[dt]);
;         }
;         ATTN_SB();
;     }
;     {
;         {
;             const int sw = (fr >> 2) * 2 + ((fr >> 1) & 1);
;             const LAS unsigned char* k0 = ckl + kk0 * 128 + ((fq ^ sw) << 4); const LAS unsigned char* k1 = ckl + kk0 * 128 + (((fq + 4) ^ sw) << 4);
; #pragma unroll
;             for (int j = 0; j < 8; ++j)
; #pragma unroll
;                 for (int t = 0; t < 2; ++t) { fb[j * 4 + t * 2] = *(const LAS bf16x8*)(k0 + j * 4096 + t * 512); fb[j * 4 + t * 2 + 1] = *(const LAS bf16x8*)(k1 + j * 4096 + t * 512); }
;         }
	s_nop 0
	v_mfma_f32_16x16x32_bf16 v[120:123], v[136:139], v[120:123], 0
	s_waitcnt vmcnt(30)
	v_mfma_f32_16x16x32_bf16 v[124:127], v[136:139], v[124:127], 0
	s_waitcnt vmcnt(29)
	v_mfma_f32_16x16x32_bf16 v[128:131], v[136:139], v[128:131], 0
	s_waitcnt vmcnt(28)
	v_mfma_f32_16x16x32_bf16 v[132:135], v[136:139], v[132:135], 0
	v_cvt_pk_bf16_f32 v136, v171, v148
	v_cvt_pk_bf16_f32 v137, v174, v179
	v_cvt_pk_bf16_f32 v138, v183, v178
	v_cvt_pk_bf16_f32 v139, v142, v140
	s_waitcnt vmcnt(27)
	s_nop 0
	v_mfma_f32_16x16x32_bf16 v[104:107], v[136:139], v[104:107], v[120:123]
	s_nop 2
	v_cvt_pk_bf16_f32 v120, v184, v185
	v_cvt_pk_bf16_f32 v121, v188, v189
	v_cvt_pk_bf16_f32 v122, v198, v182
	v_cvt_pk_bf16_f32 v123, v146, v141
	s_waitcnt vmcnt(26)
	v_mfma_f32_16x16x32_bf16 v[108:111], v[136:139], v[108:111], v[124:127]
	s_waitcnt vmcnt(23)
	v_mfma_f32_16x16x32_bf16 v[88:91], v[120:123], v[88:91], v[104:107]
	s_nop 2
	v_cvt_pk_bf16_f32 v104, v199, v200
	v_cvt_pk_bf16_f32 v105, v214, v193
	v_cvt_pk_bf16_f32 v106, v215, v175
	v_cvt_pk_bf16_f32 v107, v150, v143
	v_mfma_f32_16x16x32_bf16 v[112:115], v[136:139], v[112:115], v[128:131]
	v_mfma_f32_16x16x32_bf16 v[116:119], v[136:139], v[116:119], v[132:135]
	s_waitcnt vmcnt(19)
	v_mfma_f32_16x16x32_bf16 v[72:75], v[104:107], v[72:75], v[88:91]
	s_nop 2
	v_cvt_pk_bf16_f32 v88, v180, v216
	v_cvt_pk_bf16_f32 v89, v186, v187
	v_cvt_pk_bf16_f32 v90, v152, v153
	v_cvt_pk_bf16_f32 v91, v154, v217
	v_mfma_f32_16x16x32_bf16 v[92:95], v[120:123], v[92:95], v[108:111]
	v_mfma_f32_16x16x32_bf16 v[96:99], v[120:123], v[96:99], v[112:115]
	v_mfma_f32_16x16x32_bf16 v[100:103], v[120:123], v[100:103], v[116:119]
	s_waitcnt vmcnt(15)
	v_mfma_f32_16x16x32_bf16 v[56:59], v[88:91], v[56:59], v[72:75]
	s_nop 2
	v_cvt_pk_bf16_f32 v72, v176, v181
	v_cvt_pk_bf16_f32 v73, v190, v191
	v_cvt_pk_bf16_f32 v74, v156, v157
	v_cvt_pk_bf16_f32 v75, v158, v218
	v_mfma_f32_16x16x32_bf16 v[76:79], v[104:107], v[76:79], v[92:95]
	v_mfma_f32_16x16x32_bf16 v[80:83], v[104:107], v[80:83], v[96:99]
	v_mfma_f32_16x16x32_bf16 v[84:87], v[104:107], v[84:87], v[100:103]
	s_waitcnt vmcnt(11)
	v_mfma_f32_16x16x32_bf16 v[40:43], v[72:75], v[40:43], v[56:59]
	s_nop 2
	v_cvt_pk_bf16_f32 v56, v172, v177
	v_cvt_pk_bf16_f32 v57, v194, v192
	v_cvt_pk_bf16_f32 v58, v160, v161
	v_cvt_pk_bf16_f32 v59, v162, v144
	v_mfma_f32_16x16x32_bf16 v[60:63], v[88:91], v[60:63], v[76:79]
	v_mfma_f32_16x16x32_bf16 v[64:67], v[88:91], v[64:67], v[80:83]
	v_mfma_f32_16x16x32_bf16 v[68:71], v[88:91], v[68:71], v[84:87]
	s_waitcnt vmcnt(10)
	v_mfma_f32_16x16x32_bf16 v[44:47], v[72:75], v[44:47], v[60:63]
	s_waitcnt vmcnt(9)
	v_mfma_f32_16x16x32_bf16 v[48:51], v[72:75], v[48:51], v[64:67]
	s_waitcnt vmcnt(8)
	v_mfma_f32_16x16x32_bf16 v[52:55], v[72:75], v[52:55], v[68:71]
	s_waitcnt vmcnt(7)
	v_mfma_f32_16x16x32_bf16 v[24:27], v[56:59], v[24:27], v[40:43]
	s_nop 2
	v_cvt_pk_bf16_f32 v40, v168, v169
	v_cvt_pk_bf16_f32 v41, v170, v195
	v_cvt_pk_bf16_f32 v42, v164, v165
	v_cvt_pk_bf16_f32 v43, v166, v145
	s_waitcnt vmcnt(6)
	v_mfma_f32_16x16x32_bf16 v[28:31], v[56:59], v[28:31], v[44:47]
	s_waitcnt vmcnt(5)
	v_mfma_f32_16x16x32_bf16 v[32:35], v[56:59], v[32:35], v[48:51]
	s_waitcnt vmcnt(4)
	v_mfma_f32_16x16x32_bf16 v[36:39], v[56:59], v[36:39], v[52:55]
	s_waitcnt vmcnt(3)
	v_mfma_f32_16x16x32_bf16 v[184:187], v[40:43], v[12:15], v[24:27]
	v_add_f32_e32 v12, v164, v219
	v_add_f32_e32 v12, v165, v12
	v_add_f32_e32 v12, v166, v12
	s_waitcnt vmcnt(2)
	v_mfma_f32_16x16x32_bf16 v[214:217], v[40:43], v[16:19], v[28:31]
	v_add_f32_e32 v200, v145, v12
	s_waitcnt vmcnt(1)
	v_mfma_f32_16x16x32_bf16 v[180:183], v[40:43], v[20:23], v[32:35]
	s_waitcnt vmcnt(0)
	v_mfma_f32_16x16x32_bf16 v[188:191], v[40:43], v[8:11], v[36:39]
	v_lshlrev_b32_e32 v8, 1, v212
	v_bfe_u32 v9, v209, 1, 1
	v_lshl_add_u32 v10, v213, 7, s26
	v_bitop3_b32 v11, v8, v211, v9 bitop3:0x36
	v_add_u32_e32 v172, 4, v211
	v_lshl_add_u32 v124, v11, 4, v10
	v_bitop3_b32 v8, v8, v172, v9 bitop3:0x36
	v_lshl_add_u32 v132, v8, 4, v10
	ds_read_b128 v[8:11], v124
	ds_read_b128 v[12:15], v124 offset:512
	ds_read_b128 v[16:19], v132
	ds_read_b128 v[20:23], v132 offset:512
	ds_read_b128 v[24:27], v124 offset:4096
	ds_read_b128 v[28:31], v124 offset:4608
	ds_read_b128 v[32:35], v132 offset:4096
	ds_read_b128 v[36:39], v132 offset:4608
	ds_read_b128 v[40:43], v124 offset:8192
	ds_read_b128 v[44:47], v124 offset:8704
	ds_read_b128 v[48:51], v132 offset:8192
	ds_read_b128 v[52:55], v132 offset:8704
	ds_read_b128 v[56:59], v124 offset:12288
	ds_read_b128 v[60:63], v124 offset:12800
	ds_read_b128 v[64:67], v132 offset:12288
	ds_read_b128 v[68:71], v132 offset:12800
	ds_read_b128 v[72:75], v124 offset:16384
	ds_read_b128 v[76:79], v124 offset:16896
	ds_read_b128 v[80:83], v132 offset:16384
	ds_read_b128 v[84:87], v132 offset:16896
	ds_read_b128 v[88:91], v124 offset:20480
	ds_read_b128 v[92:95], v124 offset:20992
	ds_read_b128 v[96:99], v132 offset:20480
	ds_read_b128 v[100:103], v132 offset:20992
	ds_read_b128 v[104:107], v124 offset:24576
	ds_read_b128 v[108:111], v124 offset:25088
	ds_read_b128 v[112:115], v132 offset:24576
	ds_read_b128 v[116:119], v132 offset:25088
	ds_read_b128 v[120:123], v124 offset:28672
	ds_read_b128 v[124:127], v124 offset:29184
	ds_read_b128 v[128:131], v132 offset:28672
	ds_read_b128 v[218:221], v132 offset:29184
	s_waitcnt lgkmcnt(14)
; #define LAS __attribute__((address_space(3)))
; #define MFMA16(a, b, c) __builtin_amdgcn_mfma_f32_16x16x32_bf16((a), (b), (c), 0, 0, 0)
; #define ATTN_SB() __builtin_amdgcn_sched_barrier(0)
; __device__ __forceinline__ void attn_unit(int u, const bf16_t* KB, const bf16_t* VT, const bf16_t* QU, bf16_t* OB, const LAS float* rpb_l, LAS unsigned char* ot, const LAS unsigned char* ckl, const LAS unsigned char* cvl, int lane_) {
;     ...
; #pragma unroll
;         for (int j = 0; j < 8; ++j)
; #pragma unroll
;             for (int t = 0; t < 2; ++t) { f32x4 s = MFMA16(fb[j * 4 + t * 2], bq0, z4); s = MFMA16(fb[j * 4 + t * 2 + 1], bq1, s); st[j][t] = s; }
;         ATTN_SB();
;         {
;             const LAS unsigned char* v0 = cvl + fr * 512;
; #pragma unroll
;             for (int j = 0; j < 8; ++j) { const int xo = ((4 * j + fq) ^ fr) << 4;
; #pragma unroll
;                 for (int dt = 0; dt < 4; ++dt) fb[j * 4 + dt] = *(const LAS bf16x8*)(v0 + dt * 8192 + xo); }
;         }
;         ATTN_SB();
;         float m2 = NEG;
; #pragma unroll
;         for (int g = 0; g < 8; ++g)
; #pragma unroll
;             for (int t = 0; t < 2; ++t) m2 = fmaxf(m2, fmaxf(fmaxf(st[g][t][0], st[g][t][1]), fmaxf(st[g][t][2], st[g][t][3])));
;         m2 = fmaxf(m2, __shfl_xor(m2, 16)); m2 = fmaxf(m2, __shfl_xor(m2, 32));
	v_mfma_f32_16x16x32_bf16 v[8:11], v[8:11], v[0:3], 0
	v_mfma_f32_16x16x32_bf16 v[222:225], v[16:19], v[4:7], v[8:11]
	v_mfma_f32_16x16x32_bf16 v[8:11], v[12:15], v[0:3], 0
	v_mfma_f32_16x16x32_bf16 v[226:229], v[20:23], v[4:7], v[8:11]
	v_mfma_f32_16x16x32_bf16 v[8:11], v[24:27], v[0:3], 0
	v_mfma_f32_16x16x32_bf16 v[230:233], v[32:35], v[4:7], v[8:11]
	v_mfma_f32_16x16x32_bf16 v[8:11], v[28:31], v[0:3], 0
	v_mfma_f32_16x16x32_bf16 v[192:195], v[36:39], v[4:7], v[8:11]
	v_mfma_f32_16x16x32_bf16 v[8:11], v[40:43], v[0:3], 0
	v_mfma_f32_16x16x32_bf16 v[176:179], v[48:51], v[4:7], v[8:11]
	v_mfma_f32_16x16x32_bf16 v[8:11], v[44:47], v[0:3], 0
	v_mfma_f32_16x16x32_bf16 v[168:171], v[52:55], v[4:7], v[8:11]
	v_mfma_f32_16x16x32_bf16 v[8:11], v[56:59], v[0:3], 0
	v_mfma_f32_16x16x32_bf16 v[164:167], v[64:67], v[4:7], v[8:11]
	v_mfma_f32_16x16x32_bf16 v[8:11], v[60:63], v[0:3], 0
	v_mfma_f32_16x16x32_bf16 v[160:163], v[68:71], v[4:7], v[8:11]
	v_mfma_f32_16x16x32_bf16 v[8:11], v[72:75], v[0:3], 0
	s_waitcnt lgkmcnt(13)
	v_mfma_f32_16x16x32_bf16 v[156:159], v[80:83], v[4:7], v[8:11]
	v_mfma_f32_16x16x32_bf16 v[8:11], v[76:79], v[0:3], 0
	s_waitcnt lgkmcnt(12)
	v_mfma_f32_16x16x32_bf16 v[152:155], v[84:87], v[4:7], v[8:11]
	s_waitcnt lgkmcnt(11)
	v_mfma_f32_16x16x32_bf16 v[8:11], v[88:91], v[0:3], 0
	s_waitcnt lgkmcnt(9)
	v_mfma_f32_16x16x32_bf16 v[148:151], v[96:99], v[4:7], v[8:11]
	v_mfma_f32_16x16x32_bf16 v[8:11], v[92:95], v[0:3], 0
	s_waitcnt lgkmcnt(8)
	v_mfma_f32_16x16x32_bf16 v[144:147], v[100:103], v[4:7], v[8:11]
	s_waitcnt lgkmcnt(7)
	v_mfma_f32_16x16x32_bf16 v[8:11], v[104:107], v[0:3], 0
	s_waitcnt lgkmcnt(5)
	v_mfma_f32_16x16x32_bf16 v[140:143], v[112:115], v[4:7], v[8:11]
	v_mfma_f32_16x16x32_bf16 v[8:11], v[108:111], v[0:3], 0
	s_waitcnt lgkmcnt(4)
	v_mfma_f32_16x16x32_bf16 v[136:139], v[116:119], v[4:7], v[8:11]
	s_waitcnt lgkmcnt(3)
	v_mfma_f32_16x16x32_bf16 v[8:11], v[120:123], v[0:3], 0
	s_waitcnt lgkmcnt(2)
	v_mfma_f32_16x16x32_bf16 v[0:3], v[124:127], v[0:3], 0
	s_waitcnt lgkmcnt(1)
	v_mfma_f32_16x16x32_bf16 v[132:135], v[128:131], v[4:7], v[8:11]
	s_waitcnt lgkmcnt(0)
	v_mfma_f32_16x16x32_bf16 v[128:131], v[218:221], v[4:7], v[0:3]
	s_nop 3
	v_lshl_add_u32 v0, v210, 9, s29
	v_bitop3_b32 v1, v211, v209, 15 bitop3:0x78
	v_lshl_add_u32 v1, v1, 4, v0
	ds_read_b128 v[112:115], v1
	ds_read_b128 v[116:119], v1 offset:8192
	ds_read_b128 v[120:123], v1 offset:16384
	ds_read_b128 v[124:127], v1 offset:24576
	v_bitop3_b32 v1, v172, v209, 15 bitop3:0x78
	v_lshl_add_u32 v1, v1, 4, v0
	ds_read_b128 v[96:99], v1
	ds_read_b128 v[100:103], v1 offset:8192
	ds_read_b128 v[104:107], v1 offset:16384
	ds_read_b128 v[108:111], v1 offset:24576
	v_add_u32_e32 v1, 8, v211
	v_bitop3_b32 v1, v1, v209, 15 bitop3:0x78
	v_lshl_add_u32 v1, v1, 4, v0
	ds_read_b128 v[80:83], v1
	ds_read_b128 v[84:87], v1 offset:8192
	ds_read_b128 v[88:91], v1 offset:16384
	ds_read_b128 v[92:95], v1 offset:24576
	v_add_u32_e32 v1, 12, v211
	v_bitop3_b32 v1, v1, v209, 15 bitop3:0x78
	v_lshl_add_u32 v1, v1, 4, v0
	ds_read_b128 v[64:67], v1
	ds_read_b128 v[68:71], v1 offset:8192
	ds_read_b128 v[72:75], v1 offset:16384
	ds_read_b128 v[76:79], v1 offset:24576
	v_add_u32_e32 v1, 16, v211
	v_bitop3_b32 v1, v1, v209, 15 bitop3:0x78
	v_lshl_add_u32 v1, v1, 4, v0
	ds_read_b128 v[48:51], v1
	ds_read_b128 v[52:55], v1 offset:8192
	ds_read_b128 v[56:59], v1 offset:16384
	ds_read_b128 v[60:63], v1 offset:24576
	v_add_u32_e32 v1, 20, v211
	v_bitop3_b32 v1, v1, v209, 15 bitop3:0x78
	v_lshl_add_u32 v1, v1, 4, v0
	ds_read_b128 v[32:35], v1
	ds_read_b128 v[36:39], v1 offset:8192
	ds_read_b128 v[40:43], v1 offset:16384
	ds_read_b128 v[44:47], v1 offset:24576
	v_add_u32_e32 v1, 24, v211
	v_bitop3_b32 v1, v1, v209, 15 bitop3:0x78
	v_lshl_add_u32 v1, v1, 4, v0
	ds_read_b128 v[16:19], v1
	ds_read_b128 v[20:23], v1 offset:8192
	ds_read_b128 v[24:27], v1 offset:16384
	ds_read_b128 v[28:31], v1 offset:24576
	v_add_u32_e32 v1, 28, v211
	v_bitop3_b32 v1, v1, v209, 15 bitop3:0x78
	v_lshl_add_u32 v0, v1, 4, v0
	ds_read_b128 v[4:7], v0
	ds_read_b128 v[8:11], v0 offset:8192
	ds_read_b128 v[12:15], v0 offset:16384
	ds_read_b128 v[0:3], v0 offset:24576
	v_max3_f32 v172, v225, v222, v233
	v_max3_f32 v174, v224, v223, v232
	v_max3_f32 v175, v229, v226, v195
	v_max3_f32 v198, v228, v227, v194
	v_max3_f32 v172, v172, v230, v179
	v_max3_f32 v174, v174, v231, v178
	v_max3_f32 v175, v175, v192, v171
	v_max3_f32 v198, v198, v193, v170
	v_max3_f32 v172, v172, v176, v167
	v_max3_f32 v174, v174, v177, v166
	v_max3_f32 v175, v175, v168, v163
	v_max3_f32 v198, v198, v169, v162
	v_max3_f32 v172, v172, v164, v159
	v_max3_f32 v174, v174, v165, v158
	v_max3_f32 v175, v175, v160, v155
	v_max3_f32 v198, v198, v161, v154
	v_max3_f32 v172, v172, v156, v151
	v_max3_f32 v174, v174, v157, v150
	v_max3_f32 v175, v175, v152, v147
	v_max3_f32 v198, v198, v153, v146
	v_max3_f32 v172, v172, v148, v143
	v_max3_f32 v174, v174, v149, v142
	v_max3_f32 v175, v175, v144, v139
	v_max3_f32 v198, v198, v145, v138
	v_max3_f32 v172, v172, v140, v135
	v_max3_f32 v174, v174, v141, v134
	v_max3_f32 v175, v175, v136, v131
	v_max3_f32 v198, v198, v137, v130
	v_max_f32_e32 v172, v172, v132
	v_max_f32_e32 v174, v174, v133
	v_max_f32_e32 v175, v175, v128
	v_max_f32_e32 v198, v198, v129
	v_max3_f32 v174, v174, v175, v198
	v_max3_f32 v172, v172, s57, v174
	ds_bpermute_b32 v174, v196, v172
	v_lshlrev_b32_e32 v220, 2, v211
	s_waitcnt lgkmcnt(0)
	v_max_f32_e32 v174, v174, v174
	v_max_f32_e32 v172, v172, v174
	ds_bpermute_b32 v174, v197, v172
	s_waitcnt lgkmcnt(0)
; __device__ __forceinline__ void attn_unit(int u, const bf16_t* KB, const bf16_t* VT, const bf16_t* QU, bf16_t* OB, const LAS float* rpb_l, LAS unsigned char* ot, const LAS unsigned char* ckl, const LAS unsigned char* cvl, int lane_) {
;     ...
;         const float mn = fmaxf(m, m2);
;         const float alpha = __builtin_amdgcn_exp2f(m - mn);
;         l *= alpha;
; #pragma unroll
;         for (int e = 0; e < 4; ++e) { const float aq = __shfl(alpha, 4 * fq + e);
; #pragma unroll
;             for (int dt = 0; dt < 4; ++dt) o[dt][e] *= aq; }
; #pragma unroll
;         for (int g = 0; g < 8; ++g)
; #pragma unroll
;             for (int t = 0; t < 2; ++t)
; #pragma unroll
;                 for (int e = 0; e < 4; ++e) { const float p = __builtin_amdgcn_exp2f(st[g][t][e] - mn); st[g][t][e] = p; l += p; }
	v_max3_f32 v218, v173, v172, v174
	v_sub_f32_e32 v172, v173, v218
	v_exp_f32_e32 v219, v172
	v_and_or_b32 v172, v220, 60, v205
	v_lshlrev_b32_e32 v221, 2, v172
	v_sub_f32_e32 v192, v192, v218
	ds_bpermute_b32 v198, v221, v219
	ds_bpermute_b32 v199, v221, v219 offset:4
	ds_bpermute_b32 v212, v221, v219 offset:8
	ds_bpermute_b32 v213, v221, v219 offset:12
	v_exp_f32_e32 v192, v192
	v_sub_f32_e32 v193, v193, v218
	s_waitcnt lgkmcnt(2)
	v_pk_mul_f32 v[172:173], v[184:185], v[198:199]
	v_pk_mul_f32 v[184:185], v[214:215], v[198:199]
	v_sub_f32_e32 v214, v222, v218
	v_exp_f32_e32 v214, v214
	v_pk_mul_f32 v[180:181], v[180:181], v[198:199]
	v_pk_mul_f32 v[188:189], v[188:189], v[198:199]
	v_sub_f32_e32 v199, v223, v218
	v_fma_f32 v198, v200, v219, v214
	v_exp_f32_e32 v199, v199
	v_sub_f32_e32 v200, v224, v218
	s_waitcnt lgkmcnt(0)
	v_pk_mul_f32 v[174:175], v[186:187], v[212:213]
	v_pk_mul_f32 v[186:187], v[216:217], v[212:213]
	v_pk_mul_f32 v[182:183], v[182:183], v[212:213]
	v_pk_mul_f32 v[190:191], v[190:191], v[212:213]
	v_exp_f32_e32 v200, v200
	v_sub_f32_e32 v212, v225, v218
	v_exp_f32_e32 v212, v212
	v_sub_f32_e32 v213, v226, v218
	v_exp_f32_e32 v213, v213
	v_sub_f32_e32 v215, v227, v218
	v_add_f32_e32 v198, v199, v198
	v_exp_f32_e32 v215, v215
	v_sub_f32_e32 v216, v228, v218
	v_add_f32_e32 v198, v200, v198
	v_exp_f32_e32 v216, v216
	v_sub_f32_e32 v217, v229, v218
	v_add_f32_e32 v198, v212, v198
	v_exp_f32_e32 v217, v217
	v_sub_f32_e32 v219, v230, v218
	v_add_f32_e32 v198, v213, v198
	v_exp_f32_e32 v219, v219
	v_sub_f32_e32 v222, v231, v218
	v_add_f32_e32 v198, v215, v198
	v_exp_f32_e32 v222, v222
	v_sub_f32_e32 v223, v232, v218
	v_add_f32_e32 v198, v216, v198
	v_exp_f32_e32 v223, v223
	v_sub_f32_e32 v224, v233, v218
	v_add_f32_e32 v198, v217, v198
	v_exp_f32_e32 v224, v224
	v_add_f32_e32 v198, v219, v198
	v_add_f32_e32 v198, v222, v198
	v_exp_f32_e32 v193, v193
	v_sub_f32_e32 v194, v194, v218
	v_add_f32_e32 v198, v223, v198
	v_exp_f32_e32 v194, v194
	v_sub_f32_e32 v195, v195, v218
	v_add_f32_e32 v198, v224, v198
	v_exp_f32_e32 v195, v195
	v_sub_f32_e32 v176, v176, v218
	v_add_f32_e32 v198, v192, v198
	v_exp_f32_e32 v176, v176
	v_sub_f32_e32 v177, v177, v218
	v_add_f32_e32 v198, v193, v198
	v_exp_f32_e32 v177, v177
	v_sub_f32_e32 v178, v178, v218
	v_add_f32_e32 v198, v194, v198
	v_exp_f32_e32 v178, v178
	v_sub_f32_e32 v179, v179, v218
	v_add_f32_e32 v198, v195, v198
	v_exp_f32_e32 v179, v179
	v_sub_f32_e32 v168, v168, v218
	v_add_f32_e32 v198, v176, v198
	v_exp_f32_e32 v168, v168
	v_sub_f32_e32 v169, v169, v218
	v_add_f32_e32 v198, v177, v198
	v_exp_f32_e32 v169, v169
	v_sub_f32_e32 v170, v170, v218
	v_add_f32_e32 v198, v178, v198
	v_exp_f32_e32 v170, v170
	v_sub_f32_e32 v171, v171, v218
	v_add_f32_e32 v198, v179, v198
	v_exp_f32_e32 v171, v171
	v_sub_f32_e32 v164, v164, v218
	v_add_f32_e32 v198, v168, v198
	v_exp_f32_e32 v164, v164
	v_sub_f32_e32 v165, v165, v218
	v_add_f32_e32 v198, v169, v198
	v_exp_f32_e32 v165, v165
	v_sub_f32_e32 v166, v166, v218
	v_add_f32_e32 v198, v170, v198
	v_exp_f32_e32 v166, v166
	v_sub_f32_e32 v167, v167, v218
	v_add_f32_e32 v198, v171, v198
	v_exp_f32_e32 v167, v167
	v_sub_f32_e32 v160, v160, v218
	v_add_f32_e32 v198, v164, v198
	v_exp_f32_e32 v160, v160
	v_sub_f32_e32 v161, v161, v218
	v_add_f32_e32 v198, v165, v198
	v_exp_f32_e32 v161, v161
	v_sub_f32_e32 v162, v162, v218
	v_add_f32_e32 v198, v166, v198
	v_exp_f32_e32 v162, v162
	v_sub_f32_e32 v163, v163, v218
	v_add_f32_e32 v198, v167, v198
	v_exp_f32_e32 v163, v163
	v_sub_f32_e32 v156, v156, v218
	v_add_f32_e32 v198, v160, v198
	v_exp_f32_e32 v156, v156
	v_sub_f32_e32 v157, v157, v218
	v_add_f32_e32 v198, v161, v198
	v_exp_f32_e32 v157, v157
	v_sub_f32_e32 v158, v158, v218
	v_add_f32_e32 v198, v162, v198
	v_exp_f32_e32 v158, v158
	v_sub_f32_e32 v159, v159, v218
	v_add_f32_e32 v198, v163, v198
	v_exp_f32_e32 v159, v159
	v_sub_f32_e32 v152, v152, v218
	v_add_f32_e32 v198, v156, v198
	v_exp_f32_e32 v152, v152
	v_sub_f32_e32 v153, v153, v218
	v_add_f32_e32 v198, v157, v198
	v_exp_f32_e32 v153, v153
	v_sub_f32_e32 v154, v154, v218
	v_add_f32_e32 v198, v158, v198
	v_exp_f32_e32 v154, v154
	v_sub_f32_e32 v155, v155, v218
	v_add_f32_e32 v198, v159, v198
	v_exp_f32_e32 v155, v155
	v_sub_f32_e32 v148, v148, v218
	v_add_f32_e32 v198, v152, v198
	v_exp_f32_e32 v148, v148
	v_sub_f32_e32 v149, v149, v218
	v_add_f32_e32 v198, v153, v198
	v_exp_f32_e32 v149, v149
	v_sub_f32_e32 v150, v150, v218
	v_add_f32_e32 v198, v154, v198
	v_exp_f32_e32 v150, v150
	v_sub_f32_e32 v151, v151, v218
	v_add_f32_e32 v198, v155, v198
	v_exp_f32_e32 v151, v151
	v_sub_f32_e32 v144, v144, v218
	v_add_f32_e32 v198, v148, v198
	v_exp_f32_e32 v144, v144
	v_sub_f32_e32 v145, v145, v218
	v_add_f32_e32 v198, v149, v198
	v_exp_f32_e32 v145, v145
	v_sub_f32_e32 v146, v146, v218
	v_add_f32_e32 v198, v150, v198
	v_exp_f32_e32 v146, v146
	v_sub_f32_e32 v147, v147, v218
	v_add_f32_e32 v198, v151, v198
	v_exp_f32_e32 v147, v147
	v_sub_f32_e32 v140, v140, v218
	v_add_f32_e32 v198, v144, v198
	v_exp_f32_e32 v140, v140
	v_sub_f32_e32 v141, v141, v218
	v_add_f32_e32 v198, v145, v198
	v_exp_f32_e32 v141, v141
	v_sub_f32_e32 v142, v142, v218
	v_add_f32_e32 v198, v146, v198
	v_exp_f32_e32 v142, v142
	v_sub_f32_e32 v143, v143, v218
	v_add_f32_e32 v198, v147, v198
	v_exp_f32_e32 v143, v143
	v_sub_f32_e32 v136, v136, v218
	v_add_f32_e32 v198, v140, v198
	v_exp_f32_e32 v136, v136
	v_sub_f32_e32 v137, v137, v218
	v_add_f32_e32 v198, v141, v198
	v_exp_f32_e32 v137, v137
	v_sub_f32_e32 v138, v138, v218
	v_add_f32_e32 v198, v142, v198
	v_exp_f32_e32 v138, v138
	v_sub_f32_e32 v139, v139, v218
	v_add_f32_e32 v198, v143, v198
; __device__ __forceinline__ unsigned cvtpk_s(float lo, float hi) { f32x2_t v = {lo, hi}; bf16x2_t b = __builtin_convertvector(v, bf16x2_t); return __builtin_bit_cast(unsigned, b); }
; #define MFMA16(a, b, c) __builtin_amdgcn_mfma_f32_16x16x32_bf16((a), (b), (c), 0, 0, 0)
; #define ATTN_SB() __builtin_amdgcn_sched_barrier(0)
; __device__ __forceinline__ void attn_unit(int u, const bf16_t* KB, const bf16_t* VT, const bf16_t* QU, bf16_t* OB, const LAS float* rpb_l, LAS unsigned char* ot, const LAS unsigned char* ckl, const LAS unsigned char* cvl, int lane_) {
;     ...
;         for (int g = 0; g < 8; ++g)
; #pragma unroll
;             for (int t = 0; t < 2; ++t)
; #pragma unroll
;                 for (int e = 0; e < 4; ++e) { const float p = __builtin_amdgcn_exp2f(st[g][t][e] - mn); st[g][t][e] = p; l += p; }
;         ATTN_SB();
; #pragma unroll
;         for (int j = 0; j < 8; ++j) {
;             u32x4 pw; pw.x = cvtpk_s(st[j][0][0], st[j][0][1]); pw.y = cvtpk_s(st[j][0][2], st[j][0][3]); pw.z = cvtpk_s(st[j][1][0], st[j][1][1]); pw.w = cvtpk_s(st[j][1][2], st[j][1][3]);
;             const bf16x8 pa = __builtin_bit_cast(bf16x8, pw);
; #pragma unroll
;             for (int dt = 0; dt < 4; ++dt) o[dt] = MFMA16(pa, fb[j * 4 + dt], o[dt]);
;         }
;     }
;     __builtin_amdgcn_sched_barrier(0);
;     l += __shfl_xor(l, 16); l += __shfl_xor(l, 32);
	v_exp_f32_e32 v139, v139
	v_sub_f32_e32 v132, v132, v218
	v_add_f32_e32 v198, v136, v198
	v_exp_f32_e32 v132, v132
	v_sub_f32_e32 v133, v133, v218
	v_add_f32_e32 v198, v137, v198
	v_exp_f32_e32 v133, v133
	v_sub_f32_e32 v134, v134, v218
	v_sub_f32_e32 v128, v128, v218
	v_add_f32_e32 v198, v138, v198
	v_exp_f32_e32 v134, v134
	v_sub_f32_e32 v135, v135, v218
	v_exp_f32_e32 v225, v128
	v_sub_f32_e32 v128, v129, v218
	v_add_f32_e32 v198, v139, v198
	v_exp_f32_e32 v135, v135
	v_exp_f32_e32 v226, v128
	v_sub_f32_e32 v128, v130, v218
	v_add_f32_e32 v198, v132, v198
	v_exp_f32_e32 v227, v128
	v_sub_f32_e32 v128, v131, v218
	v_exp_f32_e32 v218, v128
	v_add_f32_e32 v128, v133, v198
	v_add_f32_e32 v128, v134, v128
	v_add_f32_e32 v198, v135, v128
	v_cvt_pk_bf16_f32 v128, v214, v199
	v_cvt_pk_bf16_f32 v129, v200, v212
	v_cvt_pk_bf16_f32 v130, v213, v215
	v_cvt_pk_bf16_f32 v131, v216, v217
	s_nop 1
	v_mfma_f32_16x16x32_bf16 v[112:115], v[128:131], v[112:115], v[172:175]
	v_mfma_f32_16x16x32_bf16 v[116:119], v[128:131], v[116:119], v[184:187]
	v_mfma_f32_16x16x32_bf16 v[120:123], v[128:131], v[120:123], v[180:183]
	v_mfma_f32_16x16x32_bf16 v[124:127], v[128:131], v[124:127], v[188:191]
	v_cvt_pk_bf16_f32 v128, v219, v222
	v_cvt_pk_bf16_f32 v129, v223, v224
	v_cvt_pk_bf16_f32 v130, v192, v193
	v_cvt_pk_bf16_f32 v131, v194, v195
	s_nop 1
	v_mfma_f32_16x16x32_bf16 v[96:99], v[128:131], v[96:99], v[112:115]
	s_nop 2
	v_cvt_pk_bf16_f32 v112, v176, v177
	v_cvt_pk_bf16_f32 v113, v178, v179
	v_cvt_pk_bf16_f32 v114, v168, v169
	v_cvt_pk_bf16_f32 v115, v170, v171
	v_mfma_f32_16x16x32_bf16 v[100:103], v[128:131], v[100:103], v[116:119]
	s_nop 0
	v_mfma_f32_16x16x32_bf16 v[80:83], v[112:115], v[80:83], v[96:99]
	s_nop 2
	v_cvt_pk_bf16_f32 v96, v164, v165
	v_cvt_pk_bf16_f32 v97, v166, v167
	v_cvt_pk_bf16_f32 v98, v160, v161
	v_cvt_pk_bf16_f32 v99, v162, v163
	v_mfma_f32_16x16x32_bf16 v[104:107], v[128:131], v[104:107], v[120:123]
	v_mfma_f32_16x16x32_bf16 v[108:111], v[128:131], v[108:111], v[124:127]
	v_mfma_f32_16x16x32_bf16 v[64:67], v[96:99], v[64:67], v[80:83]
	s_nop 2
	v_cvt_pk_bf16_f32 v80, v156, v157
	v_cvt_pk_bf16_f32 v81, v158, v159
	v_cvt_pk_bf16_f32 v82, v152, v153
	v_cvt_pk_bf16_f32 v83, v154, v155
	v_mfma_f32_16x16x32_bf16 v[84:87], v[112:115], v[84:87], v[100:103]
	v_mfma_f32_16x16x32_bf16 v[88:91], v[112:115], v[88:91], v[104:107]
	v_mfma_f32_16x16x32_bf16 v[92:95], v[112:115], v[92:95], v[108:111]
	v_mfma_f32_16x16x32_bf16 v[48:51], v[80:83], v[48:51], v[64:67]
	s_nop 2
	v_cvt_pk_bf16_f32 v64, v148, v149
	v_cvt_pk_bf16_f32 v65, v150, v151
	v_cvt_pk_bf16_f32 v66, v144, v145
	v_cvt_pk_bf16_f32 v67, v146, v147
	v_mfma_f32_16x16x32_bf16 v[68:71], v[96:99], v[68:71], v[84:87]
	v_mfma_f32_16x16x32_bf16 v[72:75], v[96:99], v[72:75], v[88:91]
	v_mfma_f32_16x16x32_bf16 v[76:79], v[96:99], v[76:79], v[92:95]
	v_mfma_f32_16x16x32_bf16 v[32:35], v[64:67], v[32:35], v[48:51]
	s_nop 2
	v_cvt_pk_bf16_f32 v48, v140, v141
	v_cvt_pk_bf16_f32 v49, v142, v143
	v_cvt_pk_bf16_f32 v50, v136, v137
	v_cvt_pk_bf16_f32 v51, v138, v139
	v_mfma_f32_16x16x32_bf16 v[52:55], v[80:83], v[52:55], v[68:71]
	v_mfma_f32_16x16x32_bf16 v[56:59], v[80:83], v[56:59], v[72:75]
	v_mfma_f32_16x16x32_bf16 v[60:63], v[80:83], v[60:63], v[76:79]
	v_mfma_f32_16x16x32_bf16 v[36:39], v[64:67], v[36:39], v[52:55]
	v_mfma_f32_16x16x32_bf16 v[40:43], v[64:67], v[40:43], v[56:59]
	v_mfma_f32_16x16x32_bf16 v[44:47], v[64:67], v[44:47], v[60:63]
	v_mfma_f32_16x16x32_bf16 v[16:19], v[48:51], v[16:19], v[32:35]
	s_nop 2
	v_cvt_pk_bf16_f32 v32, v132, v133
	v_cvt_pk_bf16_f32 v33, v134, v135
	v_cvt_pk_bf16_f32 v34, v225, v226
	v_cvt_pk_bf16_f32 v35, v227, v218
	v_mfma_f32_16x16x32_bf16 v[20:23], v[48:51], v[20:23], v[36:39]
	v_mfma_f32_16x16x32_bf16 v[24:27], v[48:51], v[24:27], v[40:43]
	v_mfma_f32_16x16x32_bf16 v[28:31], v[48:51], v[28:31], v[44:47]
	v_mfma_f32_16x16x32_bf16 v[4:7], v[32:35], v[4:7], v[16:19]
	s_nop 2
	v_add_f32_e32 v16, v225, v198
	v_add_f32_e32 v16, v226, v16
	v_add_f32_e32 v16, v227, v16
	v_mfma_f32_16x16x32_bf16 v[8:11], v[32:35], v[8:11], v[20:23]
	v_add_f32_e32 v16, v218, v16
	v_mfma_f32_16x16x32_bf16 v[12:15], v[32:35], v[12:15], v[24:27]
	v_mfma_f32_16x16x32_bf16 v[0:3], v[32:35], v[0:3], v[28:31]
	ds_bpermute_b32 v17, v196, v16
	s_waitcnt lgkmcnt(0)
; __device__ __forceinline__ unsigned short f2bf_rne(float f) { unsigned u = __float_as_uint(f); return (unsigned short)((u + 0x7fffu + ((u >> 16) & 1u)) >> 16); }
; #define LAS __attribute__((address_space(3)))
; __device__ __forceinline__ void attn_unit(int u, const bf16_t* KB, const bf16_t* VT, const bf16_t* QU, bf16_t* OB, const LAS float* rpb_l, LAS unsigned char* ot, const LAS unsigned char* ckl, const LAS unsigned char* cvl, int lane_) {
;     ...
;     l += __shfl_xor(l, 16); l += __shfl_xor(l, 32);
;     const float inv = 1.0f / l;
;     asm volatile("" ::: "memory");
; #pragma unroll
;     for (int e = 0; e < 4; ++e) { const float il = __shfl(inv, 4 * fq + e);
; #pragma unroll
;         for (int dt = 0; dt < 4; ++dt) *(LAS unsigned short*)(ot + (4 * fq + e) * 128 + (dt * 16 + fr) * 2) = pg8::f2bf_rne(o[dt][e] * il); }
;     asm volatile("" ::: "memory");
; #pragma unroll
;     for (int k = 0; k < 2; ++k) { const int p = lane + 64 * k, q = p >> 3, dc = p & 7;
;         const u32x4 w = *(const LAS u32x4*)(ot + q * 128 + dc * 16);
;         *(u32x4*)(OB + (size_t)(qrow0 + q) * 1024 + h * 64 + dc * 8) = w; }
;     asm volatile("" ::: "memory");
	v_add_f32_e32 v16, v16, v17
	ds_bpermute_b32 v17, v197, v16
	s_waitcnt lgkmcnt(0)
	v_add_f32_e32 v16, v16, v17
	v_div_scale_f32 v17, s[6:7], v16, v16, 1.0
	v_rcp_f32_e32 v18, v17
	v_div_scale_f32 v19, vcc, 1.0, v16, 1.0
	v_fma_f32 v20, -v17, v18, 1.0
	v_fmac_f32_e32 v18, v20, v18
	v_mul_f32_e32 v20, v19, v18
	v_fma_f32 v21, -v17, v20, v19
	v_fmac_f32_e32 v20, v21, v18
	v_fma_f32 v17, -v17, v20, v19
	v_div_fmas_f32 v17, v17, v18, v20
	v_div_fixup_f32 v16, v17, v16, 1.0
	ds_bpermute_b32 v17, v221, v16
	v_lshl_add_u32 v18, v210, 1, s22
	v_lshl_add_u32 v19, v211, 9, v18
	s_waitcnt lgkmcnt(0)
	v_mul_f32_e32 v4, v4, v17
	v_mul_f32_e32 v8, v8, v17
	v_mul_f32_e32 v12, v12, v17
	v_bfe_u32 v20, v4, 16, 1
	v_bfe_u32 v21, v8, 16, 1
	v_bfe_u32 v22, v12, 16, 1
	v_add3_u32 v4, v4, v20, s58
	v_add3_u32 v8, v8, v21, s58
	v_add3_u32 v12, v12, v22, s58
	ds_write_b16_d16_hi v19, v4
	ds_write_b16_d16_hi v19, v8 offset:32
	ds_write_b16_d16_hi v19, v12 offset:64
	v_or_b32_e32 v4, 1, v220
	v_and_or_b32 v8, v4, 61, v205
	v_lshlrev_b32_e32 v8, 2, v8
	ds_bpermute_b32 v8, v8, v16
	v_mul_f32_e32 v0, v0, v17
	v_bfe_u32 v12, v0, 16, 1
	v_add3_u32 v0, v0, v12, s58
	ds_write_b16_d16_hi v19, v0 offset:96
	v_lshl_add_u32 v0, v4, 7, v18
	s_waitcnt lgkmcnt(1)
	v_mul_f32_e32 v4, v5, v8
	v_bfe_u32 v5, v4, 16, 1
	v_add3_u32 v4, v4, v5, s58
	ds_write_b16_d16_hi v0, v4
	v_mul_f32_e32 v4, v9, v8
	v_bfe_u32 v5, v4, 16, 1
	v_add3_u32 v4, v4, v5, s58
	ds_write_b16_d16_hi v0, v4 offset:32
	v_mul_f32_e32 v4, v13, v8
	v_bfe_u32 v5, v4, 16, 1
	v_add3_u32 v4, v4, v5, s58
	ds_write_b16_d16_hi v0, v4 offset:64
	v_or_b32_e32 v4, 2, v220
	v_and_or_b32 v5, v4, 62, v205
	v_lshlrev_b32_e32 v5, 2, v5
	ds_bpermute_b32 v5, v5, v16
	v_mul_f32_e32 v1, v1, v8
	v_bfe_u32 v8, v1, 16, 1
	v_add3_u32 v1, v1, v8, s58
	ds_write_b16_d16_hi v0, v1 offset:96
	s_waitcnt lgkmcnt(1)
	v_mul_f32_e32 v1, v6, v5
	v_lshl_add_u32 v0, v4, 7, v18
	v_bfe_u32 v4, v1, 16, 1
	v_add3_u32 v1, v1, v4, s58
	ds_write_b16_d16_hi v0, v1
	v_mul_f32_e32 v1, v10, v5
	v_bfe_u32 v4, v1, 16, 1
	v_add3_u32 v1, v1, v4, s58
	ds_write_b16_d16_hi v0, v1 offset:32
	v_mul_f32_e32 v1, v14, v5
	v_bfe_u32 v4, v1, 16, 1
	v_add3_u32 v1, v1, v4, s58
	ds_write_b16_d16_hi v0, v1 offset:64
	v_mul_f32_e32 v1, v2, v5
	v_or_b32_e32 v2, 3, v220
	v_and_or_b32 v4, v2, 63, v205
	v_lshlrev_b32_e32 v4, 2, v4
	ds_bpermute_b32 v4, v4, v16
	v_bfe_u32 v5, v1, 16, 1
	v_add3_u32 v1, v1, v5, s58
	ds_write_b16_d16_hi v0, v1 offset:96
	v_lshl_add_u32 v0, v2, 7, v18
	s_waitcnt lgkmcnt(1)
	v_mul_f32_e32 v1, v7, v4
	v_bfe_u32 v2, v1, 16, 1
	v_add3_u32 v1, v1, v2, s58
	ds_write_b16_d16_hi v0, v1
	v_mul_f32_e32 v1, v11, v4
	v_bfe_u32 v2, v1, 16, 1
	v_add3_u32 v1, v1, v2, s58
	ds_write_b16_d16_hi v0, v1 offset:32
	v_mul_f32_e32 v1, v15, v4
	v_bfe_u32 v2, v1, 16, 1
	v_add3_u32 v1, v1, v2, s58
	ds_write_b16_d16_hi v0, v1 offset:64
	v_mul_f32_e32 v1, v3, v4
	v_bfe_u32 v2, v1, 16, 1
	v_add3_u32 v1, v1, v2, s58
	ds_write_b16_d16_hi v0, v1 offset:96
	v_lshlrev_b32_e32 v0, 4, v209
	v_and_b32_e32 v200, 0x70, v0
	v_add_u32_e32 v6, s22, v200
	v_ashrrev_i32_e32 v4, 3, v209
	v_lshl_add_u32 v0, v4, 7, v6
	v_add_u32_e32 v4, s16, v4
	v_ashrrev_i32_e32 v5, 31, v4
	v_lshl_add_u64 v[8:9], s[14:15], 0, v[200:201]
	ds_read_b128 v[0:3], v0
	v_lshlrev_b64 v[4:5], 11, v[4:5]
	v_lshl_add_u64 v[10:11], v[8:9], 0, v[4:5]
	v_add_u32_e32 v4, 64, v209
	v_ashrrev_i32_e32 v12, 3, v4
	v_lshl_add_u32 v4, v12, 7, v6
	ds_read_b128 v[4:7], v4
	s_waitcnt lgkmcnt(1)
	global_store_dwordx4 v[10:11], v[0:3], off
	s_nop 1
	v_add_u32_e32 v0, s16, v12
	v_ashrrev_i32_e32 v1, 31, v0
	v_lshlrev_b64 v[0:1], 11, v[0:1]
	v_lshl_add_u64 v[0:1], v[8:9], 0, v[0:1]
	s_waitcnt lgkmcnt(0)
	global_store_dwordx4 v[0:1], v[4:7], off
